# on top of the coalesced epilogue stores: accumulator zeroing removed in P4,P5,P7,P8,P9 (peeled first K-iteration, first MFMA of each accumulator takes C=0)
# speedup vs baseline: 1.0132x; 1.0034x over previous
; #define PG8_STAGE(bufoff, gbase, voff) do { _Pragma("unroll") for (int _i = 0; _i < 2; ++_i) \
;         __builtin_amdgcn_global_load_lds((const unsigned*)((const char*)(gbase) + (voff)[_i]), (PG8_LAS unsigned*)(lds + (bufoff) + ldsw + _i * 8192), 16, 0, 0); } while (0)
; #define PG8_LDA(dst, b, h) do { _Pragma("unroll") for (int m = 0; m < 4; ++m) _Pragma("unroll") for (int k = 0; k < 2; ++k) dst[m][k] = *(const PG8_LAS bf16x8*)(lds + PG8_SA(b, h) + aoff + m * 2048 + k * 1024); } while (0)
; #define PG8_LDB(dst, b, h) do { _Pragma("unroll") for (int n = 0; n < 2; ++n) _Pragma("unroll") for (int k = 0; k < 2; ++k) dst[n][k] = *(const PG8_LAS bf16x8*)(lds + PG8_SB(b, h) + boff + n * 2048 + k * 1024); } while (0)
; #define PG8_WAIT_V(n) asm volatile("s_waitcnt vmcnt(" #n ")" ::: "memory")
; #define PG8_WAIT_L(n) asm volatile("s_waitcnt lgkmcnt(" #n ")" ::: "memory")
; #define PG8_BAR __builtin_amdgcn_s_barrier()
; #define PG8_SCHED __builtin_amdgcn_sched_barrier(0)
; template <class Epi, class Sched, bool ALIGN_EPI = false, bool SP2 = false>
; __device__ __forceinline__ void gemm_phase(PG8_LAS unsigned char* lds, const Gemm g, const Sched& S, const Epi& E, const int wv  ) {
;     ...
;         const bool has_next = S.next(ui + 1, nxt);
;         const char* nA = has_next ? (const char*)g.A + (size_t)nxt.pm * tstep : cA; const char* nB = has_next ? (const char*)g.Bt + (size_t)nxt.pn * tstep : cB;
;         for (int t = 0; t < nt; t += 2) {
;             const bool last = (t == nt - 2);
;             const char* a1 = cA + (size_t)(t + 1) * kstep;
;             const char* a2 = last ? nA : cA + (size_t)(t + 2) * kstep; const char* b2 = last ? nB : cB + (size_t)(t + 2) * kstep;
;             const char* a3 = a2 + kstep; const char* b3 = b2 + kstep;
;             if (last && has_next) S.a_ready(nxt);
;             if constexpr (SP2) {
;             PG8_LDB(B0, 0, 0); PG8_LDB(B1, 0, 1); PG8_SCHED; PG8_LDA(At, 0, 0); PG8_STAGE(PG8_SA(1, 1), a1 + hstep, voffA);
;             PG8_WAIT_V(8); PG8_WAIT_L(0); PG8_BAR; PG8_MMA(0, 0, At, B0); PG8_MMA(0, 1, At, B1); PG8_BAR; PG8_SCHED;
;             PG8_LDA(At, 0, 1); PG8_STAGE(PG8_SB(0, 0), b2, voffB); PG8_STAGE(PG8_SB(0, 1), b2 + hstep, voffB); PG8_STAGE(PG8_SA(0, 0), a2, voffA);
;             PG8_WAIT_V(8); PG8_WAIT_L(0); PG8_BAR; PG8_MMA(1, 0, At, B0); PG8_MMA(1, 1, At, B1); PG8_BAR; PG8_SCHED;
.LBB0_915:
	s_ashr_i32 s25, s24, 31
	s_lshl_b64 s[26:27], s[24:25], 19
	s_add_u32 s26, s2, s26
	s_addc_u32 s27, s3, s27
	s_and_b64 s[28:29], s[6:7], exec
	s_cselect_b32 s25, s27, s35
	s_cselect_b32 s31, s26, s34
	s_ashr_i32 s23, s22, 31
	s_lshl_b64 s[28:29], s[22:23], 19
	s_add_u32 s28, s20, s28
	s_addc_u32 s29, s21, s29
	s_and_b64 s[38:39], s[6:7], exec
	s_cselect_b32 s23, s29, s37
	s_cselect_b32 s52, s28, s36
	s_add_u32 s34, s34, 0x40080
	s_addc_u32 s35, s35, 0
	s_add_u32 s53, s36, 0x100
	s_addc_u32 s54, s37, 0
	s_mov_b32 s55, -2
	s_waitcnt lgkmcnt(0)
	ds_read_b128 v[128:131], v191
	ds_read_b128 v[132:135], v191 offset:1024
	ds_read_b128 v[136:139], v191 offset:2048
	ds_read_b128 v[140:143], v191 offset:3072
	ds_read_b128 v[144:147], v192
	ds_read_b128 v[148:151], v192 offset:1024
	ds_read_b128 v[168:171], v192 offset:2048
	ds_read_b128 v[172:175], v192 offset:3072
	s_add_u32 s36, s34, 0xfffc0080
	s_addc_u32 s37, s35, -1
	s_cmp_eq_u32 s55, 12
	s_cselect_b32 s39, s25, s37
	s_cselect_b32 s38, s31, s36
	s_cselect_b32 s37, s23, s54
	s_cselect_b32 s36, s52, s53
	v_lshl_add_u64 v[184:185], s[34:35], 0, v[160:161]
	s_add_i32 m0, s40, 0xc000
	ds_read_b128 v[176:179], v193
	ds_read_b128 v[180:183], v193 offset:1024
	ds_read_b128 v[194:197], v193 offset:2048
	ds_read_b128 v[198:201], v193 offset:3072
	ds_read_b128 v[202:205], v193 offset:4096
	ds_read_b128 v[206:209], v193 offset:5120
	ds_read_b128 v[214:217], v193 offset:6144
	ds_read_b128 v[218:221], v193 offset:7168
	global_load_lds_dwordx4 v[184:185], off
	v_lshl_add_u64 v[184:185], s[34:35], 0, v[162:163]
	s_add_i32 m0, s40, 0xe000
	s_nop 0
	global_load_lds_dwordx4 v[184:185], off
	s_waitcnt vmcnt(8)
	s_waitcnt lgkmcnt(0)
	s_barrier
	s_setprio 1
	s_waitcnt lgkmcnt(0)
	v_mfma_f32_16x16x32_bf16 v[124:127], v[128:131], v[176:179], 0
	v_mfma_f32_16x16x32_bf16 v[120:123], v[136:139], v[176:179], 0
	v_mfma_f32_16x16x32_bf16 v[108:111], v[128:131], v[194:197], 0
	v_mfma_f32_16x16x32_bf16 v[104:107], v[136:139], v[194:197], 0
	v_mfma_f32_16x16x32_bf16 v[92:95], v[128:131], v[202:205], 0
	v_mfma_f32_16x16x32_bf16 v[88:91], v[136:139], v[202:205], 0
	v_mfma_f32_16x16x32_bf16 v[76:79], v[128:131], v[214:217], 0
	v_mfma_f32_16x16x32_bf16 v[72:75], v[136:139], v[214:217], 0
	v_mfma_f32_16x16x32_bf16 v[124:127], v[132:135], v[180:183], v[124:127]
	v_mfma_f32_16x16x32_bf16 v[120:123], v[140:143], v[180:183], v[120:123]
	v_mfma_f32_16x16x32_bf16 v[108:111], v[132:135], v[198:201], v[108:111]
	v_mfma_f32_16x16x32_bf16 v[104:107], v[140:143], v[198:201], v[104:107]
	v_mfma_f32_16x16x32_bf16 v[92:95], v[132:135], v[206:209], v[92:95]
	v_mfma_f32_16x16x32_bf16 v[88:91], v[140:143], v[206:209], v[88:91]
	v_mfma_f32_16x16x32_bf16 v[76:79], v[132:135], v[218:221], v[76:79]
	v_mfma_f32_16x16x32_bf16 v[72:75], v[140:143], v[218:221], v[72:75]
	s_setprio 0
	s_setprio 1
	v_mfma_f32_16x16x32_bf16 v[116:119], v[144:147], v[176:179], 0
	v_mfma_f32_16x16x32_bf16 v[112:115], v[168:171], v[176:179], 0
	v_mfma_f32_16x16x32_bf16 v[100:103], v[144:147], v[194:197], 0
	v_mfma_f32_16x16x32_bf16 v[96:99], v[168:171], v[194:197], 0
	v_mfma_f32_16x16x32_bf16 v[84:87], v[144:147], v[202:205], 0
	v_mfma_f32_16x16x32_bf16 v[80:83], v[168:171], v[202:205], 0
	v_mfma_f32_16x16x32_bf16 v[68:71], v[144:147], v[214:217], 0
	v_mfma_f32_16x16x32_bf16 v[64:67], v[168:171], v[214:217], 0
	v_mfma_f32_16x16x32_bf16 v[116:119], v[148:151], v[180:183], v[116:119]
	v_mfma_f32_16x16x32_bf16 v[112:115], v[172:175], v[180:183], v[112:115]
	v_mfma_f32_16x16x32_bf16 v[100:103], v[148:151], v[198:201], v[100:103]
	v_mfma_f32_16x16x32_bf16 v[96:99], v[172:175], v[198:201], v[96:99]
	v_mfma_f32_16x16x32_bf16 v[84:87], v[148:151], v[206:209], v[84:87]
	v_mfma_f32_16x16x32_bf16 v[80:83], v[172:175], v[206:209], v[80:83]
	v_mfma_f32_16x16x32_bf16 v[68:71], v[148:151], v[218:221], v[68:71]
	v_mfma_f32_16x16x32_bf16 v[64:67], v[172:175], v[218:221], v[64:67]
	s_setprio 0
	s_barrier
	s_add_i32 s56, s49, s33
	v_lshl_add_u64 v[184:185], s[36:37], 0, v[154:155]
	s_mov_b32 m0, s56
	ds_read_b128 v[176:179], v193 offset:16384
	ds_read_b128 v[180:183], v193 offset:17408
	ds_read_b128 v[194:197], v193 offset:18432
	ds_read_b128 v[198:201], v193 offset:19456
	ds_read_b128 v[202:205], v193 offset:20480
	ds_read_b128 v[206:209], v193 offset:21504
	ds_read_b128 v[214:217], v193 offset:22528
	ds_read_b128 v[218:221], v193 offset:23552
	global_load_lds_dwordx4 v[184:185], off
	s_add_i32 m0, s56, 0x2000
	s_add_u32 s56, s36, 0x40000
	v_lshl_add_u64 v[210:211], s[36:37], 0, v[158:159]
	s_addc_u32 s57, s37, 0
	s_add_i32 s58, s50, s33
	global_load_lds_dwordx4 v[210:211], off
	v_lshl_add_u64 v[222:223], s[56:57], 0, v[154:155]
	s_mov_b32 m0, s58
	v_lshl_add_u64 v[224:225], s[38:39], 0, v[156:157]
	global_load_lds_dwordx4 v[222:223], off
	v_lshl_add_u64 v[222:223], s[56:57], 0, v[158:159]
	s_add_i32 m0, s58, 0x2000
	s_nop 0
	global_load_lds_dwordx4 v[222:223], off
	v_lshl_add_u64 v[222:223], s[38:39], 0, v[152:153]
	s_mov_b32 m0, s40
	s_nop 0
	global_load_lds_dwordx4 v[222:223], off
	s_mov_b32 m0, s41
	s_nop 0
	global_load_lds_dwordx4 v[224:225], off
	s_waitcnt vmcnt(8)
	s_waitcnt lgkmcnt(0)
	s_barrier
; #define PG8_STAGE(bufoff, gbase, voff) do { _Pragma("unroll") for (int _i = 0; _i < 2; ++_i) \
;         __builtin_amdgcn_global_load_lds((const unsigned*)((const char*)(gbase) + (voff)[_i]), (PG8_LAS unsigned*)(lds + (bufoff) + ldsw + _i * 8192), 16, 0, 0); } while (0)
; #define PG8_LDA(dst, b, h) do { _Pragma("unroll") for (int m = 0; m < 4; ++m) _Pragma("unroll") for (int k = 0; k < 2; ++k) dst[m][k] = *(const PG8_LAS bf16x8*)(lds + PG8_SA(b, h) + aoff + m * 2048 + k * 1024); } while (0)
; #define PG8_LDB(dst, b, h) do { _Pragma("unroll") for (int n = 0; n < 2; ++n) _Pragma("unroll") for (int k = 0; k < 2; ++k) dst[n][k] = *(const PG8_LAS bf16x8*)(lds + PG8_SB(b, h) + boff + n * 2048 + k * 1024); } while (0)
; #define PG8_MMA(ai, bj, At, Bt) do { __builtin_amdgcn_s_setprio(1); _Pragma("unroll") for (int m = 0; m < 4; ++m) _Pragma("unroll") for (int n = 0; n < 2; ++n) _Pragma("unroll") for (int k = 0; k < 2; ++k) \
;         acc[ai][bj][m][n] = __builtin_amdgcn_mfma_f32_16x16x32_bf16(Bt[n][k], At[m][k], acc[ai][bj][m][n], 0, 0, 0); __builtin_amdgcn_s_setprio(0); } while (0)
; #define PG8_WAIT_V(n) asm volatile("s_waitcnt vmcnt(" #n ")" ::: "memory")
; #define PG8_WAIT_L(n) asm volatile("s_waitcnt lgkmcnt(" #n ")" ::: "memory")
; #define PG8_BAR __builtin_amdgcn_s_barrier()
; #define PG8_SCHED __builtin_amdgcn_sched_barrier(0)
; template <class Epi, class Sched, bool ALIGN_EPI = false, bool SP2 = false>
; __device__ __forceinline__ void gemm_phase(PG8_LAS unsigned char* lds, const Gemm g, const Sched& S, const Epi& E, const int wv  ) {
;     ...
;             PG8_WAIT_V(8); PG8_WAIT_L(0); PG8_BAR; PG8_MMA(0, 0, At, B0); PG8_MMA(0, 1, At, B1); PG8_BAR; PG8_SCHED;
;             PG8_LDA(At, 0, 1); PG8_STAGE(PG8_SB(0, 0), b2, voffB); PG8_STAGE(PG8_SB(0, 1), b2 + hstep, voffB); PG8_STAGE(PG8_SA(0, 0), a2, voffA);
;             PG8_WAIT_V(8); PG8_WAIT_L(0); PG8_BAR; PG8_MMA(1, 0, At, B0); PG8_MMA(1, 1, At, B1); PG8_BAR; PG8_SCHED;
;             PG8_LDB(B0, 1, 0); PG8_LDB(B1, 1, 1); PG8_SCHED; PG8_LDA(At, 1, 0); PG8_STAGE(PG8_SA(0, 1), a2 + hstep, voffA);
;             PG8_WAIT_V(8); PG8_WAIT_L(0); PG8_BAR; PG8_MMA(0, 0, At, B0); PG8_MMA(0, 1, At, B1); PG8_BAR; PG8_SCHED;
	s_setprio 1
	s_waitcnt lgkmcnt(0)
	v_mfma_f32_16x16x32_bf16 v[60:63], v[128:131], v[176:179], 0
	v_mfma_f32_16x16x32_bf16 v[56:59], v[136:139], v[176:179], 0
	v_mfma_f32_16x16x32_bf16 v[44:47], v[128:131], v[194:197], 0
	v_mfma_f32_16x16x32_bf16 v[40:43], v[136:139], v[194:197], 0
	v_mfma_f32_16x16x32_bf16 v[28:31], v[128:131], v[202:205], 0
	v_mfma_f32_16x16x32_bf16 v[24:27], v[136:139], v[202:205], 0
	v_mfma_f32_16x16x32_bf16 v[12:15], v[128:131], v[214:217], 0
	v_mfma_f32_16x16x32_bf16 v[8:11], v[136:139], v[214:217], 0
	v_mfma_f32_16x16x32_bf16 v[60:63], v[132:135], v[180:183], v[60:63]
	v_mfma_f32_16x16x32_bf16 v[56:59], v[140:143], v[180:183], v[56:59]
	v_mfma_f32_16x16x32_bf16 v[44:47], v[132:135], v[198:201], v[44:47]
	v_mfma_f32_16x16x32_bf16 v[40:43], v[140:143], v[198:201], v[40:43]
	v_mfma_f32_16x16x32_bf16 v[28:31], v[132:135], v[206:209], v[28:31]
	v_mfma_f32_16x16x32_bf16 v[24:27], v[140:143], v[206:209], v[24:27]
	v_mfma_f32_16x16x32_bf16 v[12:15], v[132:135], v[218:221], v[12:15]
	v_mfma_f32_16x16x32_bf16 v[8:11], v[140:143], v[218:221], v[8:11]
	s_setprio 0
	s_setprio 1
	v_mfma_f32_16x16x32_bf16 v[52:55], v[144:147], v[176:179], 0
	v_mfma_f32_16x16x32_bf16 v[48:51], v[168:171], v[176:179], 0
	v_mfma_f32_16x16x32_bf16 v[36:39], v[144:147], v[194:197], 0
	v_mfma_f32_16x16x32_bf16 v[32:35], v[168:171], v[194:197], 0
	v_mfma_f32_16x16x32_bf16 v[20:23], v[144:147], v[202:205], 0
	v_mfma_f32_16x16x32_bf16 v[16:19], v[168:171], v[202:205], 0
	v_mfma_f32_16x16x32_bf16 v[4:7], v[144:147], v[214:217], 0
	v_mfma_f32_16x16x32_bf16 v[0:3], v[168:171], v[214:217], 0
	v_mfma_f32_16x16x32_bf16 v[52:55], v[148:151], v[180:183], v[52:55]
	v_mfma_f32_16x16x32_bf16 v[48:51], v[172:175], v[180:183], v[48:51]
	v_mfma_f32_16x16x32_bf16 v[36:39], v[148:151], v[198:201], v[36:39]
	v_mfma_f32_16x16x32_bf16 v[32:35], v[172:175], v[198:201], v[32:35]
	v_mfma_f32_16x16x32_bf16 v[20:23], v[148:151], v[206:209], v[20:23]
	v_mfma_f32_16x16x32_bf16 v[16:19], v[172:175], v[206:209], v[16:19]
	v_mfma_f32_16x16x32_bf16 v[4:7], v[148:151], v[218:221], v[4:7]
	v_mfma_f32_16x16x32_bf16 v[0:3], v[172:175], v[218:221], v[0:3]
	s_setprio 0
	s_barrier
	s_add_i32 s56, 0, 0x18000
	s_add_i32 s57, 0, 0x1c000
	v_add_u32_e32 v140, s56, v189
	v_add_u32_e32 v172, s57, v189
	ds_read_b128 v[128:131], v140
	ds_read_b128 v[132:135], v140 offset:1024
	ds_read_b128 v[136:139], v140 offset:2048
	ds_read_b128 v[140:143], v140 offset:3072
	ds_read_b128 v[144:147], v172
	ds_read_b128 v[148:151], v172 offset:1024
	ds_read_b128 v[168:171], v172 offset:2048
	ds_read_b128 v[172:175], v172 offset:3072
	s_add_u32 s38, s38, 0x40000
	s_addc_u32 s39, s39, 0
	s_mov_b32 m0, s42
	v_lshl_add_u64 v[226:227], s[38:39], 0, v[152:153]
	ds_read_b128 v[176:179], v193 offset:32768
	ds_read_b128 v[180:183], v193 offset:33792
	ds_read_b128 v[194:197], v193 offset:34816
	ds_read_b128 v[198:201], v193 offset:35840
	ds_read_b128 v[202:205], v193 offset:36864
	ds_read_b128 v[206:209], v193 offset:37888
	ds_read_b128 v[214:217], v193 offset:38912
	ds_read_b128 v[218:221], v193 offset:39936
	global_load_lds_dwordx4 v[226:227], off
	v_lshl_add_u64 v[226:227], s[38:39], 0, v[156:157]
	s_mov_b32 m0, s43
	s_nop 0
	global_load_lds_dwordx4 v[226:227], off
	s_waitcnt vmcnt(8)
	s_waitcnt lgkmcnt(0)
	s_barrier
	s_setprio 1
	s_waitcnt lgkmcnt(0)
	v_mfma_f32_16x16x32_bf16 v[124:127], v[128:131], v[176:179], v[124:127]
	v_mfma_f32_16x16x32_bf16 v[120:123], v[136:139], v[176:179], v[120:123]
	v_mfma_f32_16x16x32_bf16 v[108:111], v[128:131], v[194:197], v[108:111]
	v_mfma_f32_16x16x32_bf16 v[104:107], v[136:139], v[194:197], v[104:107]
	v_mfma_f32_16x16x32_bf16 v[92:95], v[128:131], v[202:205], v[92:95]
	v_mfma_f32_16x16x32_bf16 v[88:91], v[136:139], v[202:205], v[88:91]
	v_mfma_f32_16x16x32_bf16 v[76:79], v[128:131], v[214:217], v[76:79]
	v_mfma_f32_16x16x32_bf16 v[72:75], v[136:139], v[214:217], v[72:75]
	v_mfma_f32_16x16x32_bf16 v[124:127], v[132:135], v[180:183], v[124:127]
	v_mfma_f32_16x16x32_bf16 v[120:123], v[140:143], v[180:183], v[120:123]
	v_mfma_f32_16x16x32_bf16 v[108:111], v[132:135], v[198:201], v[108:111]
	v_mfma_f32_16x16x32_bf16 v[104:107], v[140:143], v[198:201], v[104:107]
	v_mfma_f32_16x16x32_bf16 v[92:95], v[132:135], v[206:209], v[92:95]
	v_mfma_f32_16x16x32_bf16 v[88:91], v[140:143], v[206:209], v[88:91]
	v_mfma_f32_16x16x32_bf16 v[76:79], v[132:135], v[218:221], v[76:79]
	v_mfma_f32_16x16x32_bf16 v[72:75], v[140:143], v[218:221], v[72:75]
	s_setprio 0
	s_setprio 1
	v_mfma_f32_16x16x32_bf16 v[116:119], v[144:147], v[176:179], v[116:119]
	v_mfma_f32_16x16x32_bf16 v[112:115], v[168:171], v[176:179], v[112:115]
	v_mfma_f32_16x16x32_bf16 v[100:103], v[144:147], v[194:197], v[100:103]
	v_mfma_f32_16x16x32_bf16 v[96:99], v[168:171], v[194:197], v[96:99]
	v_mfma_f32_16x16x32_bf16 v[84:87], v[144:147], v[202:205], v[84:87]
	v_mfma_f32_16x16x32_bf16 v[80:83], v[168:171], v[202:205], v[80:83]
	v_mfma_f32_16x16x32_bf16 v[68:71], v[144:147], v[214:217], v[68:71]
	v_mfma_f32_16x16x32_bf16 v[64:67], v[168:171], v[214:217], v[64:67]
	v_mfma_f32_16x16x32_bf16 v[116:119], v[148:151], v[180:183], v[116:119]
	v_mfma_f32_16x16x32_bf16 v[112:115], v[172:175], v[180:183], v[112:115]
	v_mfma_f32_16x16x32_bf16 v[100:103], v[148:151], v[198:201], v[100:103]
	v_mfma_f32_16x16x32_bf16 v[96:99], v[172:175], v[198:201], v[96:99]
	v_mfma_f32_16x16x32_bf16 v[84:87], v[148:151], v[206:209], v[84:87]
	v_mfma_f32_16x16x32_bf16 v[80:83], v[172:175], v[206:209], v[80:83]
	v_mfma_f32_16x16x32_bf16 v[68:71], v[148:151], v[218:221], v[68:71]
	v_mfma_f32_16x16x32_bf16 v[64:67], v[172:175], v[218:221], v[64:67]
	s_setprio 0
	s_barrier
; #define PG8_STAGE(bufoff, gbase, voff) do { _Pragma("unroll") for (int _i = 0; _i < 2; ++_i) \
;         __builtin_amdgcn_global_load_lds((const unsigned*)((const char*)(gbase) + (voff)[_i]), (PG8_LAS unsigned*)(lds + (bufoff) + ldsw + _i * 8192), 16, 0, 0); } while (0)
; #define PG8_LDA(dst, b, h) do { _Pragma("unroll") for (int m = 0; m < 4; ++m) _Pragma("unroll") for (int k = 0; k < 2; ++k) dst[m][k] = *(const PG8_LAS bf16x8*)(lds + PG8_SA(b, h) + aoff + m * 2048 + k * 1024); } while (0)
; #define PG8_MMA(ai, bj, At, Bt) do { __builtin_amdgcn_s_setprio(1); _Pragma("unroll") for (int m = 0; m < 4; ++m) _Pragma("unroll") for (int n = 0; n < 2; ++n) _Pragma("unroll") for (int k = 0; k < 2; ++k) \
;         acc[ai][bj][m][n] = __builtin_amdgcn_mfma_f32_16x16x32_bf16(Bt[n][k], At[m][k], acc[ai][bj][m][n], 0, 0, 0); __builtin_amdgcn_s_setprio(0); } while (0)
; #define PG8_WAIT_V(n) asm volatile("s_waitcnt vmcnt(" #n ")" ::: "memory")
; #define PG8_WAIT_L(n) asm volatile("s_waitcnt lgkmcnt(" #n ")" ::: "memory")
; #define PG8_BAR __builtin_amdgcn_s_barrier()
; #define PG8_SCHED __builtin_amdgcn_sched_barrier(0)
; template <class Epi, class Sched, bool ALIGN_EPI = false, bool SP2 = false>
; __device__ __forceinline__ void gemm_phase(PG8_LAS unsigned char* lds, const Gemm g, const Sched& S, const Epi& E, const int wv  ) {
;     ...
;         for (int t = 0; t < nt; t += 2) {
;     ...
;             PG8_LDA(At, 1, 1); PG8_STAGE(PG8_SB(1, 0), b3, voffB); PG8_STAGE(PG8_SB(1, 1), b3 + hstep, voffB); PG8_STAGE(PG8_SA(1, 0), a3, voffA);
;             PG8_WAIT_V(8); PG8_WAIT_L(0); PG8_BAR; PG8_MMA(1, 0, At, B0); PG8_MMA(1, 1, At, B1); PG8_BAR; PG8_SCHED;
	s_add_i32 s38, s56, s33
	v_lshl_add_u64 v[184:185], v[184:185], 0, s[16:17]
	s_mov_b32 m0, s38
	ds_read_b128 v[176:179], v193 offset:49152
	ds_read_b128 v[180:183], v193 offset:50176
	ds_read_b128 v[194:197], v193 offset:51200
	ds_read_b128 v[198:201], v193 offset:52224
	ds_read_b128 v[202:205], v193 offset:53248
	ds_read_b128 v[206:209], v193 offset:54272
	ds_read_b128 v[214:217], v193 offset:55296
	ds_read_b128 v[218:221], v193 offset:56320
	global_load_lds_dwordx4 v[184:185], off
	s_add_i32 m0, s38, 0x2000
	s_add_u32 s36, s36, 0x40080
	v_lshl_add_u64 v[184:185], v[210:211], 0, s[16:17]
	s_addc_u32 s37, s37, 0
	s_add_i32 s38, s57, s33
	global_load_lds_dwordx4 v[184:185], off
	v_lshl_add_u64 v[184:185], s[36:37], 0, v[154:155]
	s_mov_b32 m0, s38
	s_nop 0
	global_load_lds_dwordx4 v[184:185], off
	v_lshl_add_u64 v[184:185], s[36:37], 0, v[158:159]
	s_add_i32 m0, s38, 0x2000
	s_nop 0
	global_load_lds_dwordx4 v[184:185], off
	v_lshl_add_u64 v[184:185], v[222:223], 0, s[16:17]
	s_mov_b32 m0, s47
	s_nop 0
	global_load_lds_dwordx4 v[184:185], off
	v_lshl_add_u64 v[184:185], v[224:225], 0, s[16:17]
	s_mov_b32 m0, s48
	s_nop 0
	global_load_lds_dwordx4 v[184:185], off
	s_waitcnt vmcnt(8)
	s_waitcnt lgkmcnt(0)
	s_barrier
	s_setprio 1
	s_waitcnt lgkmcnt(0)
	v_mfma_f32_16x16x32_bf16 v[60:63], v[128:131], v[176:179], v[60:63]
	v_mfma_f32_16x16x32_bf16 v[56:59], v[136:139], v[176:179], v[56:59]
	v_mfma_f32_16x16x32_bf16 v[44:47], v[128:131], v[194:197], v[44:47]
	v_mfma_f32_16x16x32_bf16 v[40:43], v[136:139], v[194:197], v[40:43]
	v_mfma_f32_16x16x32_bf16 v[28:31], v[128:131], v[202:205], v[28:31]
	v_mfma_f32_16x16x32_bf16 v[24:27], v[136:139], v[202:205], v[24:27]
	v_mfma_f32_16x16x32_bf16 v[12:15], v[128:131], v[214:217], v[12:15]
	v_mfma_f32_16x16x32_bf16 v[8:11], v[136:139], v[214:217], v[8:11]
	v_mfma_f32_16x16x32_bf16 v[60:63], v[132:135], v[180:183], v[60:63]
	v_mfma_f32_16x16x32_bf16 v[56:59], v[140:143], v[180:183], v[56:59]
	v_mfma_f32_16x16x32_bf16 v[44:47], v[132:135], v[198:201], v[44:47]
	v_mfma_f32_16x16x32_bf16 v[40:43], v[140:143], v[198:201], v[40:43]
	v_mfma_f32_16x16x32_bf16 v[28:31], v[132:135], v[206:209], v[28:31]
	v_mfma_f32_16x16x32_bf16 v[24:27], v[140:143], v[206:209], v[24:27]
	v_mfma_f32_16x16x32_bf16 v[12:15], v[132:135], v[218:221], v[12:15]
	v_mfma_f32_16x16x32_bf16 v[8:11], v[140:143], v[218:221], v[8:11]
	s_setprio 0
	s_setprio 1
	v_mfma_f32_16x16x32_bf16 v[52:55], v[144:147], v[176:179], v[52:55]
	v_mfma_f32_16x16x32_bf16 v[48:51], v[168:171], v[176:179], v[48:51]
	v_mfma_f32_16x16x32_bf16 v[36:39], v[144:147], v[194:197], v[36:39]
	v_mfma_f32_16x16x32_bf16 v[32:35], v[168:171], v[194:197], v[32:35]
	v_mfma_f32_16x16x32_bf16 v[20:23], v[144:147], v[202:205], v[20:23]
	v_mfma_f32_16x16x32_bf16 v[16:19], v[168:171], v[202:205], v[16:19]
	v_mfma_f32_16x16x32_bf16 v[4:7], v[144:147], v[214:217], v[4:7]
	v_mfma_f32_16x16x32_bf16 v[0:3], v[168:171], v[214:217], v[0:3]
	v_mfma_f32_16x16x32_bf16 v[52:55], v[148:151], v[180:183], v[52:55]
	v_mfma_f32_16x16x32_bf16 v[48:51], v[172:175], v[180:183], v[48:51]
	v_mfma_f32_16x16x32_bf16 v[36:39], v[148:151], v[198:201], v[36:39]
	v_mfma_f32_16x16x32_bf16 v[32:35], v[172:175], v[198:201], v[32:35]
	v_mfma_f32_16x16x32_bf16 v[20:23], v[148:151], v[206:209], v[20:23]
	v_mfma_f32_16x16x32_bf16 v[16:19], v[172:175], v[206:209], v[16:19]
	v_mfma_f32_16x16x32_bf16 v[4:7], v[148:151], v[218:221], v[4:7]
	v_mfma_f32_16x16x32_bf16 v[0:3], v[172:175], v[218:221], v[0:3]
	s_setprio 0
	s_barrier
	s_add_i32 s55, s55, 2
	s_add_u32 s34, s34, 0x100
	s_addc_u32 s35, s35, 0
	s_add_u32 s53, s53, 0x100
	s_addc_u32 s54, s54, 0
	s_cmp_gt_u32 s55, 13

; #define PG8_STAGE(bufoff, gbase, voff) do { _Pragma("unroll") for (int _i = 0; _i < 2; ++_i) \
;         __builtin_amdgcn_global_load_lds((const unsigned*)((const char*)(gbase) + (voff)[_i]), (PG8_LAS unsigned*)(lds + (bufoff) + ldsw + _i * 8192), 16, 0, 0); } while (0)
; #define PG8_LDA(dst, b, h) do { _Pragma("unroll") for (int m = 0; m < 4; ++m) _Pragma("unroll") for (int k = 0; k < 2; ++k) dst[m][k] = *(const PG8_LAS bf16x8*)(lds + PG8_SA(b, h) + aoff + m * 2048 + k * 1024); } while (0)
; #define PG8_LDB(dst, b, h) do { _Pragma("unroll") for (int n = 0; n < 2; ++n) _Pragma("unroll") for (int k = 0; k < 2; ++k) dst[n][k] = *(const PG8_LAS bf16x8*)(lds + PG8_SB(b, h) + boff + n * 2048 + k * 1024); } while (0)
; #define PG8_MMA(ai, bj, At, Bt) do { __builtin_amdgcn_s_setprio(1); _Pragma("unroll") for (int m = 0; m < 4; ++m) _Pragma("unroll") for (int n = 0; n < 2; ++n) _Pragma("unroll") for (int k = 0; k < 2; ++k) \
;         acc[ai][bj][m][n] = __builtin_amdgcn_mfma_f32_16x16x32_bf16(Bt[n][k], At[m][k], acc[ai][bj][m][n], 0, 0, 0); __builtin_amdgcn_s_setprio(0); } while (0)
; template <class Epi, class Sched, bool ALIGN_EPI = false, bool SP2 = false>
; __device__ __forceinline__ void gemm_phase(PG8_LAS unsigned char* lds, const Gemm g, const Sched& S, const Epi& E, const int wv  ) {
;     ...
;         const bool has_next = S.next(ui + 1, nxt);
;         const char* nA = has_next ? (const char*)g.A + (size_t)nxt.pm * tstep : cA; const char* nB = has_next ? (const char*)g.Bt + (size_t)nxt.pn * tstep : cB;
;         for (int t = 0; t < nt; t += 2) {
;             const bool last = (t == nt - 2);
;             const char* a1 = cA + (size_t)(t + 1) * kstep;
;             const char* a2 = last ? nA : cA + (size_t)(t + 2) * kstep; const char* b2 = last ? nB : cB + (size_t)(t + 2) * kstep;
;             const char* a3 = a2 + kstep; const char* b3 = b2 + kstep;
;             if (last && has_next) S.a_ready(nxt);
;             if constexpr (SP2) {
;             PG8_LDB(B0, 0, 0); PG8_LDB(B1, 0, 1); PG8_SCHED; PG8_LDA(At, 0, 0); PG8_STAGE(PG8_SA(1, 1), a1 + hstep, voffA);
;             PG8_WAIT_V(8); PG8_WAIT_L(0); PG8_BAR; PG8_MMA(0, 0, At, B0); PG8_MMA(0, 1, At, B1); PG8_BAR; PG8_SCHED;
;             PG8_LDA(At, 0, 1); PG8_STAGE(PG8_SB(0, 0), b2, voffB); PG8_STAGE(PG8_SB(0, 1), b2 + hstep, voffB); PG8_STAGE(PG8_SA(0, 0), a2, voffA);
.LBB0_1035:
	s_ashr_i32 s29, s28, 31
	s_lshl_b64 s[30:31], s[28:29], 19
	s_add_u32 s30, s21, s30
	s_addc_u32 s31, s33, s31
	s_and_b64 s[34:35], s[4:5], exec
	s_cselect_b32 s7, s31, s1
	s_cselect_b32 s9, s30, s0
	s_ashr_i32 s27, s26, 31
	s_lshl_b64 s[34:35], s[26:27], 19
	s_add_u32 s34, s42, s34
	s_addc_u32 s35, s43, s35
	s_and_b64 s[40:41], s[4:5], exec
	s_cselect_b32 s18, s35, s39
	s_cselect_b32 s25, s34, s38
	s_add_u32 s0, s0, 0x40080
	s_addc_u32 s1, s1, 0
	s_add_u32 s27, s38, 0x100
	s_addc_u32 s29, s39, 0
	s_mov_b32 s56, -2
	ds_read_b128 v[144:147], v152
	ds_read_b128 v[158:161], v152 offset:1024
	ds_read_b128 v[162:165], v152 offset:2048
	ds_read_b128 v[166:169], v152 offset:3072
	ds_read_b128 v[170:173], v153
	ds_read_b128 v[174:177], v153 offset:1024
	ds_read_b128 v[178:181], v153 offset:2048
	ds_read_b128 v[182:185], v153 offset:3072
	s_add_u32 s38, s0, 0xfffc0080
	s_addc_u32 s39, s1, -1
	s_cmp_eq_u32 s56, 12
	s_cselect_b32 s41, s7, s39
	s_cselect_b32 s40, s9, s38
	s_cselect_b32 s39, s18, s29
	s_cselect_b32 s38, s25, s27
	v_lshl_add_u64 v[210:211], s[0:1], 0, v[136:137]
	s_add_i32 m0, s44, 0xc000
	ds_read_b128 v[186:189], v154
	ds_read_b128 v[190:193], v154 offset:1024
	ds_read_b128 v[194:197], v154 offset:2048
	ds_read_b128 v[198:201], v154 offset:3072
	ds_read_b128 v[202:205], v154 offset:4096
	ds_read_b128 v[206:209], v154 offset:5120
	ds_read_b128 v[214:217], v154 offset:6144
	ds_read_b128 v[218:221], v154 offset:7168
	global_load_lds_dwordx4 v[210:211], off
	v_lshl_add_u64 v[210:211], s[0:1], 0, v[138:139]
	s_add_i32 m0, s44, 0xe000
	s_nop 0
	global_load_lds_dwordx4 v[210:211], off
	s_waitcnt vmcnt(8)
	s_waitcnt lgkmcnt(0)
	s_barrier
	s_setprio 1
	s_waitcnt lgkmcnt(0)
	v_mfma_f32_16x16x32_bf16 v[124:127], v[144:147], v[186:189], 0
	v_mfma_f32_16x16x32_bf16 v[120:123], v[162:165], v[186:189], 0
	v_mfma_f32_16x16x32_bf16 v[108:111], v[144:147], v[194:197], 0
	v_mfma_f32_16x16x32_bf16 v[104:107], v[162:165], v[194:197], 0
	v_mfma_f32_16x16x32_bf16 v[92:95], v[144:147], v[202:205], 0
	v_mfma_f32_16x16x32_bf16 v[88:91], v[162:165], v[202:205], 0
	v_mfma_f32_16x16x32_bf16 v[76:79], v[144:147], v[214:217], 0
	v_mfma_f32_16x16x32_bf16 v[72:75], v[162:165], v[214:217], 0
	v_mfma_f32_16x16x32_bf16 v[124:127], v[158:161], v[190:193], v[124:127]
	v_mfma_f32_16x16x32_bf16 v[120:123], v[166:169], v[190:193], v[120:123]
	v_mfma_f32_16x16x32_bf16 v[108:111], v[158:161], v[198:201], v[108:111]
	v_mfma_f32_16x16x32_bf16 v[104:107], v[166:169], v[198:201], v[104:107]
	v_mfma_f32_16x16x32_bf16 v[92:95], v[158:161], v[206:209], v[92:95]
	v_mfma_f32_16x16x32_bf16 v[88:91], v[166:169], v[206:209], v[88:91]
	v_mfma_f32_16x16x32_bf16 v[76:79], v[158:161], v[218:221], v[76:79]
	v_mfma_f32_16x16x32_bf16 v[72:75], v[166:169], v[218:221], v[72:75]
	s_setprio 0
	s_setprio 1
	v_mfma_f32_16x16x32_bf16 v[116:119], v[170:173], v[186:189], 0
	v_mfma_f32_16x16x32_bf16 v[112:115], v[178:181], v[186:189], 0
	v_mfma_f32_16x16x32_bf16 v[100:103], v[170:173], v[194:197], 0
	v_mfma_f32_16x16x32_bf16 v[96:99], v[178:181], v[194:197], 0
	v_mfma_f32_16x16x32_bf16 v[84:87], v[170:173], v[202:205], 0
	v_mfma_f32_16x16x32_bf16 v[80:83], v[178:181], v[202:205], 0
	v_mfma_f32_16x16x32_bf16 v[68:71], v[170:173], v[214:217], 0
	v_mfma_f32_16x16x32_bf16 v[64:67], v[178:181], v[214:217], 0
	v_mfma_f32_16x16x32_bf16 v[116:119], v[174:177], v[190:193], v[116:119]
	v_mfma_f32_16x16x32_bf16 v[112:115], v[182:185], v[190:193], v[112:115]
	v_mfma_f32_16x16x32_bf16 v[100:103], v[174:177], v[198:201], v[100:103]
	v_mfma_f32_16x16x32_bf16 v[96:99], v[182:185], v[198:201], v[96:99]
	v_mfma_f32_16x16x32_bf16 v[84:87], v[174:177], v[206:209], v[84:87]
	v_mfma_f32_16x16x32_bf16 v[80:83], v[182:185], v[206:209], v[80:83]
	v_mfma_f32_16x16x32_bf16 v[68:71], v[174:177], v[218:221], v[68:71]
	v_mfma_f32_16x16x32_bf16 v[64:67], v[182:185], v[218:221], v[64:67]
	s_setprio 0
	s_barrier
	s_add_i32 s57, s51, s20
	v_lshl_add_u64 v[210:211], s[38:39], 0, v[130:131]
	s_mov_b32 m0, s57
	ds_read_b128 v[186:189], v154 offset:16384
	ds_read_b128 v[190:193], v154 offset:17408
	ds_read_b128 v[194:197], v154 offset:18432
	ds_read_b128 v[198:201], v154 offset:19456
	ds_read_b128 v[202:205], v154 offset:20480
	ds_read_b128 v[206:209], v154 offset:21504
	ds_read_b128 v[214:217], v154 offset:22528
	ds_read_b128 v[218:221], v154 offset:23552
	global_load_lds_dwordx4 v[210:211], off
	s_add_i32 m0, s57, 0x2000
	s_add_u32 s58, s38, 0x40000
	v_lshl_add_u64 v[222:223], s[38:39], 0, v[134:135]
	s_addc_u32 s59, s39, 0
	s_add_i32 s57, s52, s20
	global_load_lds_dwordx4 v[222:223], off
	v_lshl_add_u64 v[224:225], s[58:59], 0, v[130:131]
	s_mov_b32 m0, s57
	v_lshl_add_u64 v[226:227], s[40:41], 0, v[132:133]
	global_load_lds_dwordx4 v[224:225], off
	v_lshl_add_u64 v[224:225], s[58:59], 0, v[134:135]
	s_add_i32 m0, s57, 0x2000
	s_nop 0
	global_load_lds_dwordx4 v[224:225], off
	v_lshl_add_u64 v[224:225], s[40:41], 0, v[128:129]
	s_mov_b32 m0, s44
	s_nop 0
	global_load_lds_dwordx4 v[224:225], off
	s_mov_b32 m0, s45
	s_nop 0
	global_load_lds_dwordx4 v[226:227], off
	s_waitcnt vmcnt(8)
	s_waitcnt lgkmcnt(0)
	s_barrier
; #define PG8_STAGE(bufoff, gbase, voff) do { _Pragma("unroll") for (int _i = 0; _i < 2; ++_i) \
;         __builtin_amdgcn_global_load_lds((const unsigned*)((const char*)(gbase) + (voff)[_i]), (PG8_LAS unsigned*)(lds + (bufoff) + ldsw + _i * 8192), 16, 0, 0); } while (0)
; #define PG8_LDA(dst, b, h) do { _Pragma("unroll") for (int m = 0; m < 4; ++m) _Pragma("unroll") for (int k = 0; k < 2; ++k) dst[m][k] = *(const PG8_LAS bf16x8*)(lds + PG8_SA(b, h) + aoff + m * 2048 + k * 1024); } while (0)
; #define PG8_LDB(dst, b, h) do { _Pragma("unroll") for (int n = 0; n < 2; ++n) _Pragma("unroll") for (int k = 0; k < 2; ++k) dst[n][k] = *(const PG8_LAS bf16x8*)(lds + PG8_SB(b, h) + boff + n * 2048 + k * 1024); } while (0)
; #define PG8_MMA(ai, bj, At, Bt) do { __builtin_amdgcn_s_setprio(1); _Pragma("unroll") for (int m = 0; m < 4; ++m) _Pragma("unroll") for (int n = 0; n < 2; ++n) _Pragma("unroll") for (int k = 0; k < 2; ++k) \
;         acc[ai][bj][m][n] = __builtin_amdgcn_mfma_f32_16x16x32_bf16(Bt[n][k], At[m][k], acc[ai][bj][m][n], 0, 0, 0); __builtin_amdgcn_s_setprio(0); } while (0)
; #define PG8_WAIT_V(n) asm volatile("s_waitcnt vmcnt(" #n ")" ::: "memory")
; #define PG8_WAIT_L(n) asm volatile("s_waitcnt lgkmcnt(" #n ")" ::: "memory")
; #define PG8_BAR __builtin_amdgcn_s_barrier()
; #define PG8_SCHED __builtin_amdgcn_sched_barrier(0)
; template <class Epi, class Sched, bool ALIGN_EPI = false, bool SP2 = false>
; __device__ __forceinline__ void gemm_phase(PG8_LAS unsigned char* lds, const Gemm g, const Sched& S, const Epi& E, const int wv  ) {
;     ...
;             PG8_WAIT_V(8); PG8_WAIT_L(0); PG8_BAR; PG8_MMA(1, 0, At, B0); PG8_MMA(1, 1, At, B1); PG8_BAR; PG8_SCHED;
;             PG8_LDB(B0, 1, 0); PG8_LDB(B1, 1, 1); PG8_SCHED; PG8_LDA(At, 1, 0); PG8_STAGE(PG8_SA(0, 1), a2 + hstep, voffA);
;             PG8_WAIT_V(8); PG8_WAIT_L(0); PG8_BAR; PG8_MMA(0, 0, At, B0); PG8_MMA(0, 1, At, B1); PG8_BAR; PG8_SCHED;
	s_setprio 1
	s_waitcnt lgkmcnt(0)
	v_mfma_f32_16x16x32_bf16 v[60:63], v[144:147], v[186:189], 0
	v_mfma_f32_16x16x32_bf16 v[56:59], v[162:165], v[186:189], 0
	v_mfma_f32_16x16x32_bf16 v[44:47], v[144:147], v[194:197], 0
	v_mfma_f32_16x16x32_bf16 v[40:43], v[162:165], v[194:197], 0
	v_mfma_f32_16x16x32_bf16 v[28:31], v[144:147], v[202:205], 0
	v_mfma_f32_16x16x32_bf16 v[24:27], v[162:165], v[202:205], 0
	v_mfma_f32_16x16x32_bf16 v[12:15], v[144:147], v[214:217], 0
	v_mfma_f32_16x16x32_bf16 v[8:11], v[162:165], v[214:217], 0
	v_mfma_f32_16x16x32_bf16 v[60:63], v[158:161], v[190:193], v[60:63]
	v_mfma_f32_16x16x32_bf16 v[56:59], v[166:169], v[190:193], v[56:59]
	v_mfma_f32_16x16x32_bf16 v[44:47], v[158:161], v[198:201], v[44:47]
	v_mfma_f32_16x16x32_bf16 v[40:43], v[166:169], v[198:201], v[40:43]
	v_mfma_f32_16x16x32_bf16 v[28:31], v[158:161], v[206:209], v[28:31]
	v_mfma_f32_16x16x32_bf16 v[24:27], v[166:169], v[206:209], v[24:27]
	v_mfma_f32_16x16x32_bf16 v[12:15], v[158:161], v[218:221], v[12:15]
	v_mfma_f32_16x16x32_bf16 v[8:11], v[166:169], v[218:221], v[8:11]
	s_setprio 0
	s_setprio 1
	v_mfma_f32_16x16x32_bf16 v[52:55], v[170:173], v[186:189], 0
	v_mfma_f32_16x16x32_bf16 v[48:51], v[178:181], v[186:189], 0
	v_mfma_f32_16x16x32_bf16 v[36:39], v[170:173], v[194:197], 0
	v_mfma_f32_16x16x32_bf16 v[32:35], v[178:181], v[194:197], 0
	v_mfma_f32_16x16x32_bf16 v[20:23], v[170:173], v[202:205], 0
	v_mfma_f32_16x16x32_bf16 v[16:19], v[178:181], v[202:205], 0
	v_mfma_f32_16x16x32_bf16 v[4:7], v[170:173], v[214:217], 0
	v_mfma_f32_16x16x32_bf16 v[0:3], v[178:181], v[214:217], 0
	v_mfma_f32_16x16x32_bf16 v[52:55], v[174:177], v[190:193], v[52:55]
	v_mfma_f32_16x16x32_bf16 v[48:51], v[182:185], v[190:193], v[48:51]
	v_mfma_f32_16x16x32_bf16 v[36:39], v[174:177], v[198:201], v[36:39]
	v_mfma_f32_16x16x32_bf16 v[32:35], v[182:185], v[198:201], v[32:35]
	v_mfma_f32_16x16x32_bf16 v[20:23], v[174:177], v[206:209], v[20:23]
	v_mfma_f32_16x16x32_bf16 v[16:19], v[182:185], v[206:209], v[16:19]
	v_mfma_f32_16x16x32_bf16 v[4:7], v[174:177], v[218:221], v[4:7]
	v_mfma_f32_16x16x32_bf16 v[0:3], v[182:185], v[218:221], v[0:3]
	s_setprio 0
	s_barrier
	s_add_i32 s57, 0, 0x18000
	v_add_u32_e32 v157, s57, v149
	s_add_i32 s58, 0, 0x1c000
	ds_read_b128 v[144:147], v157
	ds_read_b128 v[158:161], v157 offset:1024
	ds_read_b128 v[162:165], v157 offset:2048
	ds_read_b128 v[166:169], v157 offset:3072
	v_add_u32_e32 v157, s58, v149
	ds_read_b128 v[170:173], v157
	ds_read_b128 v[174:177], v157 offset:1024
	ds_read_b128 v[178:181], v157 offset:2048
	ds_read_b128 v[182:185], v157 offset:3072
	s_add_u32 s40, s40, 0x40000
	s_addc_u32 s41, s41, 0
	s_mov_b32 m0, s46
	v_lshl_add_u64 v[228:229], s[40:41], 0, v[128:129]
	ds_read_b128 v[186:189], v154 offset:32768
	ds_read_b128 v[190:193], v154 offset:33792
	ds_read_b128 v[194:197], v154 offset:34816
	ds_read_b128 v[198:201], v154 offset:35840
	ds_read_b128 v[202:205], v154 offset:36864
	ds_read_b128 v[206:209], v154 offset:37888
	ds_read_b128 v[214:217], v154 offset:38912
	ds_read_b128 v[218:221], v154 offset:39936
	global_load_lds_dwordx4 v[228:229], off
	v_lshl_add_u64 v[228:229], s[40:41], 0, v[132:133]
	s_mov_b32 m0, s47
	s_nop 0
	global_load_lds_dwordx4 v[228:229], off
	s_waitcnt vmcnt(8)
	s_waitcnt lgkmcnt(0)
	s_barrier
	s_setprio 1
	s_waitcnt lgkmcnt(0)
	v_mfma_f32_16x16x32_bf16 v[124:127], v[144:147], v[186:189], v[124:127]
	v_mfma_f32_16x16x32_bf16 v[120:123], v[162:165], v[186:189], v[120:123]
	v_mfma_f32_16x16x32_bf16 v[108:111], v[144:147], v[194:197], v[108:111]
	v_mfma_f32_16x16x32_bf16 v[104:107], v[162:165], v[194:197], v[104:107]
	v_mfma_f32_16x16x32_bf16 v[92:95], v[144:147], v[202:205], v[92:95]
	v_mfma_f32_16x16x32_bf16 v[88:91], v[162:165], v[202:205], v[88:91]
	v_mfma_f32_16x16x32_bf16 v[76:79], v[144:147], v[214:217], v[76:79]
	v_mfma_f32_16x16x32_bf16 v[72:75], v[162:165], v[214:217], v[72:75]
	v_mfma_f32_16x16x32_bf16 v[124:127], v[158:161], v[190:193], v[124:127]
	v_mfma_f32_16x16x32_bf16 v[120:123], v[166:169], v[190:193], v[120:123]
	v_mfma_f32_16x16x32_bf16 v[108:111], v[158:161], v[198:201], v[108:111]
	v_mfma_f32_16x16x32_bf16 v[104:107], v[166:169], v[198:201], v[104:107]
	v_mfma_f32_16x16x32_bf16 v[92:95], v[158:161], v[206:209], v[92:95]
	v_mfma_f32_16x16x32_bf16 v[88:91], v[166:169], v[206:209], v[88:91]
	v_mfma_f32_16x16x32_bf16 v[76:79], v[158:161], v[218:221], v[76:79]
	v_mfma_f32_16x16x32_bf16 v[72:75], v[166:169], v[218:221], v[72:75]
	s_setprio 0
	s_setprio 1
	v_mfma_f32_16x16x32_bf16 v[116:119], v[170:173], v[186:189], v[116:119]
	v_mfma_f32_16x16x32_bf16 v[112:115], v[178:181], v[186:189], v[112:115]
	v_mfma_f32_16x16x32_bf16 v[100:103], v[170:173], v[194:197], v[100:103]
	v_mfma_f32_16x16x32_bf16 v[96:99], v[178:181], v[194:197], v[96:99]
	v_mfma_f32_16x16x32_bf16 v[84:87], v[170:173], v[202:205], v[84:87]
	v_mfma_f32_16x16x32_bf16 v[80:83], v[178:181], v[202:205], v[80:83]
	v_mfma_f32_16x16x32_bf16 v[68:71], v[170:173], v[214:217], v[68:71]
	v_mfma_f32_16x16x32_bf16 v[64:67], v[178:181], v[214:217], v[64:67]
	v_mfma_f32_16x16x32_bf16 v[116:119], v[174:177], v[190:193], v[116:119]
	v_mfma_f32_16x16x32_bf16 v[112:115], v[182:185], v[190:193], v[112:115]
	v_mfma_f32_16x16x32_bf16 v[100:103], v[174:177], v[198:201], v[100:103]
	v_mfma_f32_16x16x32_bf16 v[96:99], v[182:185], v[198:201], v[96:99]
	v_mfma_f32_16x16x32_bf16 v[84:87], v[174:177], v[206:209], v[84:87]
	v_mfma_f32_16x16x32_bf16 v[80:83], v[182:185], v[206:209], v[80:83]
	v_mfma_f32_16x16x32_bf16 v[68:71], v[174:177], v[218:221], v[68:71]
	v_mfma_f32_16x16x32_bf16 v[64:67], v[182:185], v[218:221], v[64:67]
	s_setprio 0
	s_barrier
; #define PG8_STAGE(bufoff, gbase, voff) do { _Pragma("unroll") for (int _i = 0; _i < 2; ++_i) \
;         __builtin_amdgcn_global_load_lds((const unsigned*)((const char*)(gbase) + (voff)[_i]), (PG8_LAS unsigned*)(lds + (bufoff) + ldsw + _i * 8192), 16, 0, 0); } while (0)
; #define PG8_LDA(dst, b, h) do { _Pragma("unroll") for (int m = 0; m < 4; ++m) _Pragma("unroll") for (int k = 0; k < 2; ++k) dst[m][k] = *(const PG8_LAS bf16x8*)(lds + PG8_SA(b, h) + aoff + m * 2048 + k * 1024); } while (0)
; #define PG8_MMA(ai, bj, At, Bt) do { __builtin_amdgcn_s_setprio(1); _Pragma("unroll") for (int m = 0; m < 4; ++m) _Pragma("unroll") for (int n = 0; n < 2; ++n) _Pragma("unroll") for (int k = 0; k < 2; ++k) \
;         acc[ai][bj][m][n] = __builtin_amdgcn_mfma_f32_16x16x32_bf16(Bt[n][k], At[m][k], acc[ai][bj][m][n], 0, 0, 0); __builtin_amdgcn_s_setprio(0); } while (0)
; #define PG8_WAIT_V(n) asm volatile("s_waitcnt vmcnt(" #n ")" ::: "memory")
; #define PG8_WAIT_L(n) asm volatile("s_waitcnt lgkmcnt(" #n ")" ::: "memory")
; #define PG8_BAR __builtin_amdgcn_s_barrier()
; #define PG8_SCHED __builtin_amdgcn_sched_barrier(0)
; template <class Epi, class Sched, bool ALIGN_EPI = false, bool SP2 = false>
; __device__ __forceinline__ void gemm_phase(PG8_LAS unsigned char* lds, const Gemm g, const Sched& S, const Epi& E, const int wv  ) {
;     ...
;         for (int t = 0; t < nt; t += 2) {
;     ...
;             PG8_LDA(At, 1, 1); PG8_STAGE(PG8_SB(1, 0), b3, voffB); PG8_STAGE(PG8_SB(1, 1), b3 + hstep, voffB); PG8_STAGE(PG8_SA(1, 0), a3, voffA);
;             PG8_WAIT_V(8); PG8_WAIT_L(0); PG8_BAR; PG8_MMA(1, 0, At, B0); PG8_MMA(1, 1, At, B1); PG8_BAR; PG8_SCHED;
	s_add_i32 s40, s57, s20
	v_lshl_add_u64 v[210:211], v[210:211], 0, s[16:17]
	s_mov_b32 m0, s40
	ds_read_b128 v[186:189], v154 offset:49152
	ds_read_b128 v[190:193], v154 offset:50176
	ds_read_b128 v[194:197], v154 offset:51200
	ds_read_b128 v[198:201], v154 offset:52224
	ds_read_b128 v[202:205], v154 offset:53248
	ds_read_b128 v[206:209], v154 offset:54272
	ds_read_b128 v[214:217], v154 offset:55296
	ds_read_b128 v[218:221], v154 offset:56320
	global_load_lds_dwordx4 v[210:211], off
	s_add_i32 m0, s40, 0x2000
	s_add_u32 s38, s38, 0x40080
	v_lshl_add_u64 v[210:211], v[222:223], 0, s[16:17]
	s_addc_u32 s39, s39, 0
	s_add_i32 s40, s58, s20
	global_load_lds_dwordx4 v[210:211], off
	v_lshl_add_u64 v[210:211], s[38:39], 0, v[130:131]
	s_mov_b32 m0, s40
	s_nop 0
	global_load_lds_dwordx4 v[210:211], off
	v_lshl_add_u64 v[210:211], s[38:39], 0, v[134:135]
	s_add_i32 m0, s40, 0x2000
	s_nop 0
	global_load_lds_dwordx4 v[210:211], off
	v_lshl_add_u64 v[210:211], v[224:225], 0, s[16:17]
	s_mov_b32 m0, s49
	s_nop 0
	global_load_lds_dwordx4 v[210:211], off
	v_lshl_add_u64 v[210:211], v[226:227], 0, s[16:17]
	s_mov_b32 m0, s50
	s_nop 0
	global_load_lds_dwordx4 v[210:211], off
	s_waitcnt vmcnt(8)
	s_waitcnt lgkmcnt(0)
	s_barrier
	s_setprio 1
	s_waitcnt lgkmcnt(0)
	v_mfma_f32_16x16x32_bf16 v[60:63], v[144:147], v[186:189], v[60:63]
	v_mfma_f32_16x16x32_bf16 v[56:59], v[162:165], v[186:189], v[56:59]
	v_mfma_f32_16x16x32_bf16 v[44:47], v[144:147], v[194:197], v[44:47]
	v_mfma_f32_16x16x32_bf16 v[40:43], v[162:165], v[194:197], v[40:43]
	v_mfma_f32_16x16x32_bf16 v[28:31], v[144:147], v[202:205], v[28:31]
	v_mfma_f32_16x16x32_bf16 v[24:27], v[162:165], v[202:205], v[24:27]
	v_mfma_f32_16x16x32_bf16 v[12:15], v[144:147], v[214:217], v[12:15]
	v_mfma_f32_16x16x32_bf16 v[8:11], v[162:165], v[214:217], v[8:11]
	v_mfma_f32_16x16x32_bf16 v[60:63], v[158:161], v[190:193], v[60:63]
	v_mfma_f32_16x16x32_bf16 v[56:59], v[166:169], v[190:193], v[56:59]
	v_mfma_f32_16x16x32_bf16 v[44:47], v[158:161], v[198:201], v[44:47]
	v_mfma_f32_16x16x32_bf16 v[40:43], v[166:169], v[198:201], v[40:43]
	v_mfma_f32_16x16x32_bf16 v[28:31], v[158:161], v[206:209], v[28:31]
	v_mfma_f32_16x16x32_bf16 v[24:27], v[166:169], v[206:209], v[24:27]
	v_mfma_f32_16x16x32_bf16 v[12:15], v[158:161], v[218:221], v[12:15]
	v_mfma_f32_16x16x32_bf16 v[8:11], v[166:169], v[218:221], v[8:11]
	s_setprio 0
	s_setprio 1
	v_mfma_f32_16x16x32_bf16 v[52:55], v[170:173], v[186:189], v[52:55]
	v_mfma_f32_16x16x32_bf16 v[48:51], v[178:181], v[186:189], v[48:51]
	v_mfma_f32_16x16x32_bf16 v[36:39], v[170:173], v[194:197], v[36:39]
	v_mfma_f32_16x16x32_bf16 v[32:35], v[178:181], v[194:197], v[32:35]
	v_mfma_f32_16x16x32_bf16 v[20:23], v[170:173], v[202:205], v[20:23]
	v_mfma_f32_16x16x32_bf16 v[16:19], v[178:181], v[202:205], v[16:19]
	v_mfma_f32_16x16x32_bf16 v[4:7], v[170:173], v[214:217], v[4:7]
	v_mfma_f32_16x16x32_bf16 v[0:3], v[178:181], v[214:217], v[0:3]
	v_mfma_f32_16x16x32_bf16 v[52:55], v[174:177], v[190:193], v[52:55]
	v_mfma_f32_16x16x32_bf16 v[48:51], v[182:185], v[190:193], v[48:51]
	v_mfma_f32_16x16x32_bf16 v[36:39], v[174:177], v[198:201], v[36:39]
	v_mfma_f32_16x16x32_bf16 v[32:35], v[182:185], v[198:201], v[32:35]
	v_mfma_f32_16x16x32_bf16 v[20:23], v[174:177], v[206:209], v[20:23]
	v_mfma_f32_16x16x32_bf16 v[16:19], v[182:185], v[206:209], v[16:19]
	v_mfma_f32_16x16x32_bf16 v[4:7], v[174:177], v[218:221], v[4:7]
	v_mfma_f32_16x16x32_bf16 v[0:3], v[182:185], v[218:221], v[0:3]
	s_setprio 0
	s_barrier
	s_add_i32 s56, s56, 2
	s_add_u32 s0, s0, 0x100
	s_addc_u32 s1, s1, 0
	s_add_u32 s27, s27, 0x100
	s_addc_u32 s29, s29, 0
	s_cmp_gt_u32 s56, 13

; #define PG8_STAGE(bufoff, gbase, voff) do { _Pragma("unroll") for (int _i = 0; _i < 2; ++_i) \
;         __builtin_amdgcn_global_load_lds((const unsigned*)((const char*)(gbase) + (voff)[_i]), (PG8_LAS unsigned*)(lds + (bufoff) + ldsw + _i * 8192), 16, 0, 0); } while (0)
; #define PG8_LDA(dst, b, h) do { _Pragma("unroll") for (int m = 0; m < 4; ++m) _Pragma("unroll") for (int k = 0; k < 2; ++k) dst[m][k] = *(const PG8_LAS bf16x8*)(lds + PG8_SA(b, h) + aoff + m * 2048 + k * 1024); } while (0)
; #define PG8_LDB(dst, b, h) do { _Pragma("unroll") for (int n = 0; n < 2; ++n) _Pragma("unroll") for (int k = 0; k < 2; ++k) dst[n][k] = *(const PG8_LAS bf16x8*)(lds + PG8_SB(b, h) + boff + n * 2048 + k * 1024); } while (0)
; #define PG8_MMA(ai, bj, At, Bt) do { __builtin_amdgcn_s_setprio(1); _Pragma("unroll") for (int m = 0; m < 4; ++m) _Pragma("unroll") for (int n = 0; n < 2; ++n) _Pragma("unroll") for (int k = 0; k < 2; ++k) \
;         acc[ai][bj][m][n] = __builtin_amdgcn_mfma_f32_16x16x32_bf16(Bt[n][k], At[m][k], acc[ai][bj][m][n], 0, 0, 0); __builtin_amdgcn_s_setprio(0); } while (0)
; template <class Epi, class Sched, bool ALIGN_EPI = false, bool SP2 = false>
; __device__ __forceinline__ void gemm_phase(PG8_LAS unsigned char* lds, const Gemm g, const Sched& S, const Epi& E, const int wv  ) {
;     ...
;         const bool has_next = S.next(ui + 1, nxt);
;         const char* nA = has_next ? (const char*)g.A + (size_t)nxt.pm * tstep : cA; const char* nB = has_next ? (const char*)g.Bt + (size_t)nxt.pn * tstep : cB;
;         for (int t = 0; t < nt; t += 2) {
;             const bool last = (t == nt - 2);
;             const char* a1 = cA + (size_t)(t + 1) * kstep;
;             const char* a2 = last ? nA : cA + (size_t)(t + 2) * kstep; const char* b2 = last ? nB : cB + (size_t)(t + 2) * kstep;
;             const char* a3 = a2 + kstep; const char* b3 = b2 + kstep;
;             if (last && has_next) S.a_ready(nxt);
;             if constexpr (SP2) {
;             PG8_LDB(B0, 0, 0); PG8_LDB(B1, 0, 1); PG8_SCHED; PG8_LDA(At, 0, 0); PG8_STAGE(PG8_SA(1, 1), a1 + hstep, voffA);
;             PG8_WAIT_V(8); PG8_WAIT_L(0); PG8_BAR; PG8_MMA(0, 0, At, B0); PG8_MMA(0, 1, At, B1); PG8_BAR; PG8_SCHED;
;             PG8_LDA(At, 0, 1); PG8_STAGE(PG8_SB(0, 0), b2, voffB); PG8_STAGE(PG8_SB(0, 1), b2 + hstep, voffB); PG8_STAGE(PG8_SA(0, 0), a2, voffA);
.LBB0_1214:
	s_ashr_i32 s27, s26, 31
	s_lshl_b64 s[28:29], s[26:27], 19
	s_add_u32 s28, s2, s28
	s_addc_u32 s29, s3, s29
	s_and_b64 s[30:31], s[6:7], exec
	s_cselect_b32 s27, s29, s37
	s_cselect_b32 s35, s28, s36
	s_ashr_i32 s25, s24, 31
	s_lshl_b64 s[30:31], s[24:25], 19
	s_add_u32 s30, s20, s30
	s_addc_u32 s31, s21, s31
	s_and_b64 s[40:41], s[6:7], exec
	s_cselect_b32 s25, s31, s39
	s_cselect_b32 s54, s30, s38
	s_add_u32 s36, s36, 0x40080
	s_addc_u32 s37, s37, 0
	s_add_u32 s55, s38, 0x100
	s_addc_u32 s56, s39, 0
	s_mov_b32 s57, -2
	s_waitcnt lgkmcnt(0)
	ds_read_b128 v[128:131], v191
	ds_read_b128 v[132:135], v191 offset:1024
	ds_read_b128 v[136:139], v191 offset:2048
	ds_read_b128 v[140:143], v191 offset:3072
	ds_read_b128 v[144:147], v192
	ds_read_b128 v[148:151], v192 offset:1024
	ds_read_b128 v[168:171], v192 offset:2048
	ds_read_b128 v[172:175], v192 offset:3072
	s_add_u32 s38, s36, 0xfffc0080
	s_addc_u32 s39, s37, -1
	s_cmp_eq_u32 s57, 12
	s_cselect_b32 s41, s27, s39
	s_cselect_b32 s40, s35, s38
	s_cselect_b32 s39, s25, s56
	s_cselect_b32 s38, s54, s55
	v_lshl_add_u64 v[184:185], s[36:37], 0, v[160:161]
	s_add_i32 m0, s42, 0xc000
	ds_read_b128 v[176:179], v193
	ds_read_b128 v[180:183], v193 offset:1024
	ds_read_b128 v[194:197], v193 offset:2048
	ds_read_b128 v[198:201], v193 offset:3072
	ds_read_b128 v[202:205], v193 offset:4096
	ds_read_b128 v[206:209], v193 offset:5120
	ds_read_b128 v[214:217], v193 offset:6144
	ds_read_b128 v[218:221], v193 offset:7168
	global_load_lds_dwordx4 v[184:185], off
	v_lshl_add_u64 v[184:185], s[36:37], 0, v[162:163]
	s_add_i32 m0, s42, 0xe000
	s_nop 0
	global_load_lds_dwordx4 v[184:185], off
	s_waitcnt vmcnt(8)
	s_waitcnt lgkmcnt(0)
	s_barrier
	s_setprio 1
	s_waitcnt lgkmcnt(0)
	v_mfma_f32_16x16x32_bf16 v[124:127], v[128:131], v[176:179], 0
	v_mfma_f32_16x16x32_bf16 v[120:123], v[136:139], v[176:179], 0
	v_mfma_f32_16x16x32_bf16 v[108:111], v[128:131], v[194:197], 0
	v_mfma_f32_16x16x32_bf16 v[104:107], v[136:139], v[194:197], 0
	v_mfma_f32_16x16x32_bf16 v[92:95], v[128:131], v[202:205], 0
	v_mfma_f32_16x16x32_bf16 v[88:91], v[136:139], v[202:205], 0
	v_mfma_f32_16x16x32_bf16 v[76:79], v[128:131], v[214:217], 0
	v_mfma_f32_16x16x32_bf16 v[72:75], v[136:139], v[214:217], 0
	v_mfma_f32_16x16x32_bf16 v[124:127], v[132:135], v[180:183], v[124:127]
	v_mfma_f32_16x16x32_bf16 v[120:123], v[140:143], v[180:183], v[120:123]
	v_mfma_f32_16x16x32_bf16 v[108:111], v[132:135], v[198:201], v[108:111]
	v_mfma_f32_16x16x32_bf16 v[104:107], v[140:143], v[198:201], v[104:107]
	v_mfma_f32_16x16x32_bf16 v[92:95], v[132:135], v[206:209], v[92:95]
	v_mfma_f32_16x16x32_bf16 v[88:91], v[140:143], v[206:209], v[88:91]
	v_mfma_f32_16x16x32_bf16 v[76:79], v[132:135], v[218:221], v[76:79]
	v_mfma_f32_16x16x32_bf16 v[72:75], v[140:143], v[218:221], v[72:75]
	s_setprio 0
	s_setprio 1
	v_mfma_f32_16x16x32_bf16 v[116:119], v[144:147], v[176:179], 0
	v_mfma_f32_16x16x32_bf16 v[112:115], v[168:171], v[176:179], 0
	v_mfma_f32_16x16x32_bf16 v[100:103], v[144:147], v[194:197], 0
	v_mfma_f32_16x16x32_bf16 v[96:99], v[168:171], v[194:197], 0
	v_mfma_f32_16x16x32_bf16 v[84:87], v[144:147], v[202:205], 0
	v_mfma_f32_16x16x32_bf16 v[80:83], v[168:171], v[202:205], 0
	v_mfma_f32_16x16x32_bf16 v[68:71], v[144:147], v[214:217], 0
	v_mfma_f32_16x16x32_bf16 v[64:67], v[168:171], v[214:217], 0
	v_mfma_f32_16x16x32_bf16 v[116:119], v[148:151], v[180:183], v[116:119]
	v_mfma_f32_16x16x32_bf16 v[112:115], v[172:175], v[180:183], v[112:115]
	v_mfma_f32_16x16x32_bf16 v[100:103], v[148:151], v[198:201], v[100:103]
	v_mfma_f32_16x16x32_bf16 v[96:99], v[172:175], v[198:201], v[96:99]
	v_mfma_f32_16x16x32_bf16 v[84:87], v[148:151], v[206:209], v[84:87]
	v_mfma_f32_16x16x32_bf16 v[80:83], v[172:175], v[206:209], v[80:83]
	v_mfma_f32_16x16x32_bf16 v[68:71], v[148:151], v[218:221], v[68:71]
	v_mfma_f32_16x16x32_bf16 v[64:67], v[172:175], v[218:221], v[64:67]
	s_setprio 0
	s_barrier
	s_add_i32 s58, s51, s33
	v_lshl_add_u64 v[184:185], s[38:39], 0, v[154:155]
	s_mov_b32 m0, s58
	ds_read_b128 v[176:179], v193 offset:16384
	ds_read_b128 v[180:183], v193 offset:17408
	ds_read_b128 v[194:197], v193 offset:18432
	ds_read_b128 v[198:201], v193 offset:19456
	ds_read_b128 v[202:205], v193 offset:20480
	ds_read_b128 v[206:209], v193 offset:21504
	ds_read_b128 v[214:217], v193 offset:22528
	ds_read_b128 v[218:221], v193 offset:23552
	global_load_lds_dwordx4 v[184:185], off
	s_add_i32 m0, s58, 0x2000
	s_add_u32 s58, s38, 0x40000
	v_lshl_add_u64 v[210:211], s[38:39], 0, v[158:159]
	s_addc_u32 s59, s39, 0
	s_add_i32 s60, s52, s33
	global_load_lds_dwordx4 v[210:211], off
	v_lshl_add_u64 v[222:223], s[58:59], 0, v[154:155]
	s_mov_b32 m0, s60
	v_lshl_add_u64 v[224:225], s[40:41], 0, v[156:157]
	global_load_lds_dwordx4 v[222:223], off
	v_lshl_add_u64 v[222:223], s[58:59], 0, v[158:159]
	s_add_i32 m0, s60, 0x2000
	s_nop 0
	global_load_lds_dwordx4 v[222:223], off
	v_lshl_add_u64 v[222:223], s[40:41], 0, v[152:153]
	s_mov_b32 m0, s42
	s_nop 0
	global_load_lds_dwordx4 v[222:223], off
	s_mov_b32 m0, s43
	s_nop 0
	global_load_lds_dwordx4 v[224:225], off
	s_waitcnt vmcnt(8)
	s_waitcnt lgkmcnt(0)
	s_barrier
; #define PG8_STAGE(bufoff, gbase, voff) do { _Pragma("unroll") for (int _i = 0; _i < 2; ++_i) \
;         __builtin_amdgcn_global_load_lds((const unsigned*)((const char*)(gbase) + (voff)[_i]), (PG8_LAS unsigned*)(lds + (bufoff) + ldsw + _i * 8192), 16, 0, 0); } while (0)
; #define PG8_LDA(dst, b, h) do { _Pragma("unroll") for (int m = 0; m < 4; ++m) _Pragma("unroll") for (int k = 0; k < 2; ++k) dst[m][k] = *(const PG8_LAS bf16x8*)(lds + PG8_SA(b, h) + aoff + m * 2048 + k * 1024); } while (0)
; #define PG8_LDB(dst, b, h) do { _Pragma("unroll") for (int n = 0; n < 2; ++n) _Pragma("unroll") for (int k = 0; k < 2; ++k) dst[n][k] = *(const PG8_LAS bf16x8*)(lds + PG8_SB(b, h) + boff + n * 2048 + k * 1024); } while (0)
; #define PG8_MMA(ai, bj, At, Bt) do { __builtin_amdgcn_s_setprio(1); _Pragma("unroll") for (int m = 0; m < 4; ++m) _Pragma("unroll") for (int n = 0; n < 2; ++n) _Pragma("unroll") for (int k = 0; k < 2; ++k) \
;         acc[ai][bj][m][n] = __builtin_amdgcn_mfma_f32_16x16x32_bf16(Bt[n][k], At[m][k], acc[ai][bj][m][n], 0, 0, 0); __builtin_amdgcn_s_setprio(0); } while (0)
; #define PG8_WAIT_V(n) asm volatile("s_waitcnt vmcnt(" #n ")" ::: "memory")
; #define PG8_WAIT_L(n) asm volatile("s_waitcnt lgkmcnt(" #n ")" ::: "memory")
; #define PG8_BAR __builtin_amdgcn_s_barrier()
; #define PG8_SCHED __builtin_amdgcn_sched_barrier(0)
; template <class Epi, class Sched, bool ALIGN_EPI = false, bool SP2 = false>
; __device__ __forceinline__ void gemm_phase(PG8_LAS unsigned char* lds, const Gemm g, const Sched& S, const Epi& E, const int wv  ) {
;     ...
;             PG8_WAIT_V(8); PG8_WAIT_L(0); PG8_BAR; PG8_MMA(1, 0, At, B0); PG8_MMA(1, 1, At, B1); PG8_BAR; PG8_SCHED;
;             PG8_LDB(B0, 1, 0); PG8_LDB(B1, 1, 1); PG8_SCHED; PG8_LDA(At, 1, 0); PG8_STAGE(PG8_SA(0, 1), a2 + hstep, voffA);
;             PG8_WAIT_V(8); PG8_WAIT_L(0); PG8_BAR; PG8_MMA(0, 0, At, B0); PG8_MMA(0, 1, At, B1); PG8_BAR; PG8_SCHED;
	s_setprio 1
	s_waitcnt lgkmcnt(0)
	v_mfma_f32_16x16x32_bf16 v[60:63], v[128:131], v[176:179], 0
	v_mfma_f32_16x16x32_bf16 v[56:59], v[136:139], v[176:179], 0
	v_mfma_f32_16x16x32_bf16 v[44:47], v[128:131], v[194:197], 0
	v_mfma_f32_16x16x32_bf16 v[40:43], v[136:139], v[194:197], 0
	v_mfma_f32_16x16x32_bf16 v[28:31], v[128:131], v[202:205], 0
	v_mfma_f32_16x16x32_bf16 v[24:27], v[136:139], v[202:205], 0
	v_mfma_f32_16x16x32_bf16 v[12:15], v[128:131], v[214:217], 0
	v_mfma_f32_16x16x32_bf16 v[8:11], v[136:139], v[214:217], 0
	v_mfma_f32_16x16x32_bf16 v[60:63], v[132:135], v[180:183], v[60:63]
	v_mfma_f32_16x16x32_bf16 v[56:59], v[140:143], v[180:183], v[56:59]
	v_mfma_f32_16x16x32_bf16 v[44:47], v[132:135], v[198:201], v[44:47]
	v_mfma_f32_16x16x32_bf16 v[40:43], v[140:143], v[198:201], v[40:43]
	v_mfma_f32_16x16x32_bf16 v[28:31], v[132:135], v[206:209], v[28:31]
	v_mfma_f32_16x16x32_bf16 v[24:27], v[140:143], v[206:209], v[24:27]
	v_mfma_f32_16x16x32_bf16 v[12:15], v[132:135], v[218:221], v[12:15]
	v_mfma_f32_16x16x32_bf16 v[8:11], v[140:143], v[218:221], v[8:11]
	s_setprio 0
	s_setprio 1
	v_mfma_f32_16x16x32_bf16 v[52:55], v[144:147], v[176:179], 0
	v_mfma_f32_16x16x32_bf16 v[48:51], v[168:171], v[176:179], 0
	v_mfma_f32_16x16x32_bf16 v[36:39], v[144:147], v[194:197], 0
	v_mfma_f32_16x16x32_bf16 v[32:35], v[168:171], v[194:197], 0
	v_mfma_f32_16x16x32_bf16 v[20:23], v[144:147], v[202:205], 0
	v_mfma_f32_16x16x32_bf16 v[16:19], v[168:171], v[202:205], 0
	v_mfma_f32_16x16x32_bf16 v[4:7], v[144:147], v[214:217], 0
	v_mfma_f32_16x16x32_bf16 v[0:3], v[168:171], v[214:217], 0
	v_mfma_f32_16x16x32_bf16 v[52:55], v[148:151], v[180:183], v[52:55]
	v_mfma_f32_16x16x32_bf16 v[48:51], v[172:175], v[180:183], v[48:51]
	v_mfma_f32_16x16x32_bf16 v[36:39], v[148:151], v[198:201], v[36:39]
	v_mfma_f32_16x16x32_bf16 v[32:35], v[172:175], v[198:201], v[32:35]
	v_mfma_f32_16x16x32_bf16 v[20:23], v[148:151], v[206:209], v[20:23]
	v_mfma_f32_16x16x32_bf16 v[16:19], v[172:175], v[206:209], v[16:19]
	v_mfma_f32_16x16x32_bf16 v[4:7], v[148:151], v[218:221], v[4:7]
	v_mfma_f32_16x16x32_bf16 v[0:3], v[172:175], v[218:221], v[0:3]
	s_setprio 0
	s_barrier
	s_add_i32 s58, 0, 0x18000
	s_add_i32 s59, 0, 0x1c000
	v_add_u32_e32 v140, s58, v189
	v_add_u32_e32 v172, s59, v189
	ds_read_b128 v[128:131], v140
	ds_read_b128 v[132:135], v140 offset:1024
	ds_read_b128 v[136:139], v140 offset:2048
	ds_read_b128 v[140:143], v140 offset:3072
	ds_read_b128 v[144:147], v172
	ds_read_b128 v[148:151], v172 offset:1024
	ds_read_b128 v[168:171], v172 offset:2048
	ds_read_b128 v[172:175], v172 offset:3072
	s_add_u32 s40, s40, 0x40000
	s_addc_u32 s41, s41, 0
	s_mov_b32 m0, s44
	v_lshl_add_u64 v[226:227], s[40:41], 0, v[152:153]
	ds_read_b128 v[176:179], v193 offset:32768
	ds_read_b128 v[180:183], v193 offset:33792
	ds_read_b128 v[194:197], v193 offset:34816
	ds_read_b128 v[198:201], v193 offset:35840
	ds_read_b128 v[202:205], v193 offset:36864
	ds_read_b128 v[206:209], v193 offset:37888
	ds_read_b128 v[214:217], v193 offset:38912
	ds_read_b128 v[218:221], v193 offset:39936
	global_load_lds_dwordx4 v[226:227], off
	v_lshl_add_u64 v[226:227], s[40:41], 0, v[156:157]
	s_mov_b32 m0, s45
	s_nop 0
	global_load_lds_dwordx4 v[226:227], off
	s_waitcnt vmcnt(8)
	s_waitcnt lgkmcnt(0)
	s_barrier
	s_setprio 1
	s_waitcnt lgkmcnt(0)
	v_mfma_f32_16x16x32_bf16 v[124:127], v[128:131], v[176:179], v[124:127]
	v_mfma_f32_16x16x32_bf16 v[120:123], v[136:139], v[176:179], v[120:123]
	v_mfma_f32_16x16x32_bf16 v[108:111], v[128:131], v[194:197], v[108:111]
	v_mfma_f32_16x16x32_bf16 v[104:107], v[136:139], v[194:197], v[104:107]
	v_mfma_f32_16x16x32_bf16 v[92:95], v[128:131], v[202:205], v[92:95]
	v_mfma_f32_16x16x32_bf16 v[88:91], v[136:139], v[202:205], v[88:91]
	v_mfma_f32_16x16x32_bf16 v[76:79], v[128:131], v[214:217], v[76:79]
	v_mfma_f32_16x16x32_bf16 v[72:75], v[136:139], v[214:217], v[72:75]
	v_mfma_f32_16x16x32_bf16 v[124:127], v[132:135], v[180:183], v[124:127]
	v_mfma_f32_16x16x32_bf16 v[120:123], v[140:143], v[180:183], v[120:123]
	v_mfma_f32_16x16x32_bf16 v[108:111], v[132:135], v[198:201], v[108:111]
	v_mfma_f32_16x16x32_bf16 v[104:107], v[140:143], v[198:201], v[104:107]
	v_mfma_f32_16x16x32_bf16 v[92:95], v[132:135], v[206:209], v[92:95]
	v_mfma_f32_16x16x32_bf16 v[88:91], v[140:143], v[206:209], v[88:91]
	v_mfma_f32_16x16x32_bf16 v[76:79], v[132:135], v[218:221], v[76:79]
	v_mfma_f32_16x16x32_bf16 v[72:75], v[140:143], v[218:221], v[72:75]
	s_setprio 0
	s_setprio 1
	v_mfma_f32_16x16x32_bf16 v[116:119], v[144:147], v[176:179], v[116:119]
	v_mfma_f32_16x16x32_bf16 v[112:115], v[168:171], v[176:179], v[112:115]
	v_mfma_f32_16x16x32_bf16 v[100:103], v[144:147], v[194:197], v[100:103]
	v_mfma_f32_16x16x32_bf16 v[96:99], v[168:171], v[194:197], v[96:99]
	v_mfma_f32_16x16x32_bf16 v[84:87], v[144:147], v[202:205], v[84:87]
	v_mfma_f32_16x16x32_bf16 v[80:83], v[168:171], v[202:205], v[80:83]
	v_mfma_f32_16x16x32_bf16 v[68:71], v[144:147], v[214:217], v[68:71]
	v_mfma_f32_16x16x32_bf16 v[64:67], v[168:171], v[214:217], v[64:67]
	v_mfma_f32_16x16x32_bf16 v[116:119], v[148:151], v[180:183], v[116:119]
	v_mfma_f32_16x16x32_bf16 v[112:115], v[172:175], v[180:183], v[112:115]
	v_mfma_f32_16x16x32_bf16 v[100:103], v[148:151], v[198:201], v[100:103]
	v_mfma_f32_16x16x32_bf16 v[96:99], v[172:175], v[198:201], v[96:99]
	v_mfma_f32_16x16x32_bf16 v[84:87], v[148:151], v[206:209], v[84:87]
	v_mfma_f32_16x16x32_bf16 v[80:83], v[172:175], v[206:209], v[80:83]
	v_mfma_f32_16x16x32_bf16 v[68:71], v[148:151], v[218:221], v[68:71]
	v_mfma_f32_16x16x32_bf16 v[64:67], v[172:175], v[218:221], v[64:67]
	s_setprio 0
	s_barrier
; #define PG8_STAGE(bufoff, gbase, voff) do { _Pragma("unroll") for (int _i = 0; _i < 2; ++_i) \
;         __builtin_amdgcn_global_load_lds((const unsigned*)((const char*)(gbase) + (voff)[_i]), (PG8_LAS unsigned*)(lds + (bufoff) + ldsw + _i * 8192), 16, 0, 0); } while (0)
; #define PG8_LDA(dst, b, h) do { _Pragma("unroll") for (int m = 0; m < 4; ++m) _Pragma("unroll") for (int k = 0; k < 2; ++k) dst[m][k] = *(const PG8_LAS bf16x8*)(lds + PG8_SA(b, h) + aoff + m * 2048 + k * 1024); } while (0)
; #define PG8_MMA(ai, bj, At, Bt) do { __builtin_amdgcn_s_setprio(1); _Pragma("unroll") for (int m = 0; m < 4; ++m) _Pragma("unroll") for (int n = 0; n < 2; ++n) _Pragma("unroll") for (int k = 0; k < 2; ++k) \
;         acc[ai][bj][m][n] = __builtin_amdgcn_mfma_f32_16x16x32_bf16(Bt[n][k], At[m][k], acc[ai][bj][m][n], 0, 0, 0); __builtin_amdgcn_s_setprio(0); } while (0)
; #define PG8_WAIT_V(n) asm volatile("s_waitcnt vmcnt(" #n ")" ::: "memory")
; #define PG8_WAIT_L(n) asm volatile("s_waitcnt lgkmcnt(" #n ")" ::: "memory")
; #define PG8_BAR __builtin_amdgcn_s_barrier()
; #define PG8_SCHED __builtin_amdgcn_sched_barrier(0)
; template <class Epi, class Sched, bool ALIGN_EPI = false, bool SP2 = false>
; __device__ __forceinline__ void gemm_phase(PG8_LAS unsigned char* lds, const Gemm g, const Sched& S, const Epi& E, const int wv  ) {
;     ...
;         for (int t = 0; t < nt; t += 2) {
;     ...
;             PG8_LDA(At, 1, 1); PG8_STAGE(PG8_SB(1, 0), b3, voffB); PG8_STAGE(PG8_SB(1, 1), b3 + hstep, voffB); PG8_STAGE(PG8_SA(1, 0), a3, voffA);
;             PG8_WAIT_V(8); PG8_WAIT_L(0); PG8_BAR; PG8_MMA(1, 0, At, B0); PG8_MMA(1, 1, At, B1); PG8_BAR; PG8_SCHED;
	s_add_i32 s40, s58, s33
	v_lshl_add_u64 v[184:185], v[184:185], 0, s[18:19]
	s_mov_b32 m0, s40
	ds_read_b128 v[176:179], v193 offset:49152
	ds_read_b128 v[180:183], v193 offset:50176
	ds_read_b128 v[194:197], v193 offset:51200
	ds_read_b128 v[198:201], v193 offset:52224
	ds_read_b128 v[202:205], v193 offset:53248
	ds_read_b128 v[206:209], v193 offset:54272
	ds_read_b128 v[214:217], v193 offset:55296
	ds_read_b128 v[218:221], v193 offset:56320
	global_load_lds_dwordx4 v[184:185], off
	s_add_i32 m0, s40, 0x2000
	s_add_u32 s38, s38, 0x40080
	v_lshl_add_u64 v[184:185], v[210:211], 0, s[18:19]
	s_addc_u32 s39, s39, 0
	s_add_i32 s40, s59, s33
	global_load_lds_dwordx4 v[184:185], off
	v_lshl_add_u64 v[184:185], s[38:39], 0, v[154:155]
	s_mov_b32 m0, s40
	s_nop 0
	global_load_lds_dwordx4 v[184:185], off
	v_lshl_add_u64 v[184:185], s[38:39], 0, v[158:159]
	s_add_i32 m0, s40, 0x2000
	s_nop 0
	global_load_lds_dwordx4 v[184:185], off
	v_lshl_add_u64 v[184:185], v[222:223], 0, s[18:19]
	s_mov_b32 m0, s49
	s_nop 0
	global_load_lds_dwordx4 v[184:185], off
	v_lshl_add_u64 v[184:185], v[224:225], 0, s[18:19]
	s_mov_b32 m0, s50
	s_nop 0
	global_load_lds_dwordx4 v[184:185], off
	s_waitcnt vmcnt(8)
	s_waitcnt lgkmcnt(0)
	s_barrier
	s_setprio 1
	s_waitcnt lgkmcnt(0)
	v_mfma_f32_16x16x32_bf16 v[60:63], v[128:131], v[176:179], v[60:63]
	v_mfma_f32_16x16x32_bf16 v[56:59], v[136:139], v[176:179], v[56:59]
	v_mfma_f32_16x16x32_bf16 v[44:47], v[128:131], v[194:197], v[44:47]
	v_mfma_f32_16x16x32_bf16 v[40:43], v[136:139], v[194:197], v[40:43]
	v_mfma_f32_16x16x32_bf16 v[28:31], v[128:131], v[202:205], v[28:31]
	v_mfma_f32_16x16x32_bf16 v[24:27], v[136:139], v[202:205], v[24:27]
	v_mfma_f32_16x16x32_bf16 v[12:15], v[128:131], v[214:217], v[12:15]
	v_mfma_f32_16x16x32_bf16 v[8:11], v[136:139], v[214:217], v[8:11]
	v_mfma_f32_16x16x32_bf16 v[60:63], v[132:135], v[180:183], v[60:63]
	v_mfma_f32_16x16x32_bf16 v[56:59], v[140:143], v[180:183], v[56:59]
	v_mfma_f32_16x16x32_bf16 v[44:47], v[132:135], v[198:201], v[44:47]
	v_mfma_f32_16x16x32_bf16 v[40:43], v[140:143], v[198:201], v[40:43]
	v_mfma_f32_16x16x32_bf16 v[28:31], v[132:135], v[206:209], v[28:31]
	v_mfma_f32_16x16x32_bf16 v[24:27], v[140:143], v[206:209], v[24:27]
	v_mfma_f32_16x16x32_bf16 v[12:15], v[132:135], v[218:221], v[12:15]
	v_mfma_f32_16x16x32_bf16 v[8:11], v[140:143], v[218:221], v[8:11]
	s_setprio 0
	s_setprio 1
	v_mfma_f32_16x16x32_bf16 v[52:55], v[144:147], v[176:179], v[52:55]
	v_mfma_f32_16x16x32_bf16 v[48:51], v[168:171], v[176:179], v[48:51]
	v_mfma_f32_16x16x32_bf16 v[36:39], v[144:147], v[194:197], v[36:39]
	v_mfma_f32_16x16x32_bf16 v[32:35], v[168:171], v[194:197], v[32:35]
	v_mfma_f32_16x16x32_bf16 v[20:23], v[144:147], v[202:205], v[20:23]
	v_mfma_f32_16x16x32_bf16 v[16:19], v[168:171], v[202:205], v[16:19]
	v_mfma_f32_16x16x32_bf16 v[4:7], v[144:147], v[214:217], v[4:7]
	v_mfma_f32_16x16x32_bf16 v[0:3], v[168:171], v[214:217], v[0:3]
	v_mfma_f32_16x16x32_bf16 v[52:55], v[148:151], v[180:183], v[52:55]
	v_mfma_f32_16x16x32_bf16 v[48:51], v[172:175], v[180:183], v[48:51]
	v_mfma_f32_16x16x32_bf16 v[36:39], v[148:151], v[198:201], v[36:39]
	v_mfma_f32_16x16x32_bf16 v[32:35], v[172:175], v[198:201], v[32:35]
	v_mfma_f32_16x16x32_bf16 v[20:23], v[148:151], v[206:209], v[20:23]
	v_mfma_f32_16x16x32_bf16 v[16:19], v[172:175], v[206:209], v[16:19]
	v_mfma_f32_16x16x32_bf16 v[4:7], v[148:151], v[218:221], v[4:7]
	v_mfma_f32_16x16x32_bf16 v[0:3], v[172:175], v[218:221], v[0:3]
	s_setprio 0
	s_barrier
	s_add_i32 s57, s57, 2
	s_add_u32 s36, s36, 0x100
	s_addc_u32 s37, s37, 0
	s_add_u32 s55, s55, 0x100
	s_addc_u32 s56, s56, 0
	s_cmp_gt_u32 s57, 13

; #define PG8_STAGE(bufoff, gbase, voff) do { _Pragma("unroll") for (int _i = 0; _i < 2; ++_i) \
;         __builtin_amdgcn_global_load_lds((const unsigned*)((const char*)(gbase) + (voff)[_i]), (PG8_LAS unsigned*)(lds + (bufoff) + ldsw + _i * 8192), 16, 0, 0); } while (0)
; #define PG8_LDA(dst, b, h) do { _Pragma("unroll") for (int m = 0; m < 4; ++m) _Pragma("unroll") for (int k = 0; k < 2; ++k) dst[m][k] = *(const PG8_LAS bf16x8*)(lds + PG8_SA(b, h) + aoff + m * 2048 + k * 1024); } while (0)
; #define PG8_LDB(dst, b, h) do { _Pragma("unroll") for (int n = 0; n < 2; ++n) _Pragma("unroll") for (int k = 0; k < 2; ++k) dst[n][k] = *(const PG8_LAS bf16x8*)(lds + PG8_SB(b, h) + boff + n * 2048 + k * 1024); } while (0)
; #define PG8_MMA(ai, bj, At, Bt) do { __builtin_amdgcn_s_setprio(1); _Pragma("unroll") for (int m = 0; m < 4; ++m) _Pragma("unroll") for (int n = 0; n < 2; ++n) _Pragma("unroll") for (int k = 0; k < 2; ++k) \
;         acc[ai][bj][m][n] = __builtin_amdgcn_mfma_f32_16x16x32_bf16(Bt[n][k], At[m][k], acc[ai][bj][m][n], 0, 0, 0); __builtin_amdgcn_s_setprio(0); } while (0)
; template <class Epi, class Sched, bool ALIGN_EPI = false, bool SP2 = false>
; __device__ __forceinline__ void gemm_phase(PG8_LAS unsigned char* lds, const Gemm g, const Sched& S, const Epi& E, const int wv  ) {
;     ...
;         const bool has_next = S.next(ui + 1, nxt);
;         const char* nA = has_next ? (const char*)g.A + (size_t)nxt.pm * tstep : cA; const char* nB = has_next ? (const char*)g.Bt + (size_t)nxt.pn * tstep : cB;
;         for (int t = 0; t < nt; t += 2) {
;             const bool last = (t == nt - 2);
;             const char* a1 = cA + (size_t)(t + 1) * kstep;
;             const char* a2 = last ? nA : cA + (size_t)(t + 2) * kstep; const char* b2 = last ? nB : cB + (size_t)(t + 2) * kstep;
;             const char* a3 = a2 + kstep; const char* b3 = b2 + kstep;
;             if (last && has_next) S.a_ready(nxt);
;             if constexpr (SP2) {
;             PG8_LDB(B0, 0, 0); PG8_LDB(B1, 0, 1); PG8_SCHED; PG8_LDA(At, 0, 0); PG8_STAGE(PG8_SA(1, 1), a1 + hstep, voffA);
;             PG8_WAIT_V(8); PG8_WAIT_L(0); PG8_BAR; PG8_MMA(0, 0, At, B0); PG8_MMA(0, 1, At, B1); PG8_BAR; PG8_SCHED;
;             PG8_LDA(At, 0, 1); PG8_STAGE(PG8_SB(0, 0), b2, voffB); PG8_STAGE(PG8_SB(0, 1), b2 + hstep, voffB); PG8_STAGE(PG8_SA(0, 0), a2, voffA);
.LBB0_1334:
	s_ashr_i32 s29, s28, 31
	s_lshl_b64 s[30:31], s[28:29], 19
	s_add_u32 s30, s21, s30
	s_addc_u32 s31, s33, s31
	s_and_b64 s[34:35], s[4:5], exec
	s_cselect_b32 s7, s31, s1
	s_cselect_b32 s9, s30, s0
	s_ashr_i32 s27, s26, 31
	s_lshl_b64 s[34:35], s[26:27], 19
	s_add_u32 s34, s42, s34
	s_addc_u32 s35, s43, s35
	s_and_b64 s[40:41], s[4:5], exec
	s_cselect_b32 s18, s35, s39
	s_cselect_b32 s25, s34, s38
	s_add_u32 s0, s0, 0x40080
	s_addc_u32 s1, s1, 0
	s_add_u32 s27, s38, 0x100
	s_addc_u32 s29, s39, 0
	s_mov_b32 s56, -2
	ds_read_b128 v[144:147], v153
	ds_read_b128 v[158:161], v153 offset:1024
	ds_read_b128 v[162:165], v153 offset:2048
	ds_read_b128 v[166:169], v153 offset:3072
	ds_read_b128 v[170:173], v154
	ds_read_b128 v[174:177], v154 offset:1024
	ds_read_b128 v[178:181], v154 offset:2048
	ds_read_b128 v[182:185], v154 offset:3072
	s_add_u32 s38, s0, 0xfffc0080
	s_addc_u32 s39, s1, -1
	s_cmp_eq_u32 s56, 12
	s_cselect_b32 s41, s7, s39
	s_cselect_b32 s40, s9, s38
	s_cselect_b32 s39, s18, s29
	s_cselect_b32 s38, s25, s27
	v_lshl_add_u64 v[210:211], s[0:1], 0, v[136:137]
	s_add_i32 m0, s44, 0xc000
	ds_read_b128 v[186:189], v155
	ds_read_b128 v[190:193], v155 offset:1024
	ds_read_b128 v[194:197], v155 offset:2048
	ds_read_b128 v[198:201], v155 offset:3072
	ds_read_b128 v[202:205], v155 offset:4096
	ds_read_b128 v[206:209], v155 offset:5120
	ds_read_b128 v[214:217], v155 offset:6144
	ds_read_b128 v[218:221], v155 offset:7168
	global_load_lds_dwordx4 v[210:211], off
	v_lshl_add_u64 v[210:211], s[0:1], 0, v[138:139]
	s_add_i32 m0, s44, 0xe000
	s_nop 0
	global_load_lds_dwordx4 v[210:211], off
	s_waitcnt vmcnt(8)
	s_waitcnt lgkmcnt(0)
	s_barrier
	s_setprio 1
	s_waitcnt lgkmcnt(0)
	v_mfma_f32_16x16x32_bf16 v[124:127], v[144:147], v[186:189], 0
	v_mfma_f32_16x16x32_bf16 v[120:123], v[162:165], v[186:189], 0
	v_mfma_f32_16x16x32_bf16 v[108:111], v[144:147], v[194:197], 0
	v_mfma_f32_16x16x32_bf16 v[104:107], v[162:165], v[194:197], 0
	v_mfma_f32_16x16x32_bf16 v[92:95], v[144:147], v[202:205], 0
	v_mfma_f32_16x16x32_bf16 v[88:91], v[162:165], v[202:205], 0
	v_mfma_f32_16x16x32_bf16 v[76:79], v[144:147], v[214:217], 0
	v_mfma_f32_16x16x32_bf16 v[72:75], v[162:165], v[214:217], 0
	v_mfma_f32_16x16x32_bf16 v[124:127], v[158:161], v[190:193], v[124:127]
	v_mfma_f32_16x16x32_bf16 v[120:123], v[166:169], v[190:193], v[120:123]
	v_mfma_f32_16x16x32_bf16 v[108:111], v[158:161], v[198:201], v[108:111]
	v_mfma_f32_16x16x32_bf16 v[104:107], v[166:169], v[198:201], v[104:107]
	v_mfma_f32_16x16x32_bf16 v[92:95], v[158:161], v[206:209], v[92:95]
	v_mfma_f32_16x16x32_bf16 v[88:91], v[166:169], v[206:209], v[88:91]
	v_mfma_f32_16x16x32_bf16 v[76:79], v[158:161], v[218:221], v[76:79]
	v_mfma_f32_16x16x32_bf16 v[72:75], v[166:169], v[218:221], v[72:75]
	s_setprio 0
	s_setprio 1
	v_mfma_f32_16x16x32_bf16 v[116:119], v[170:173], v[186:189], 0
	v_mfma_f32_16x16x32_bf16 v[112:115], v[178:181], v[186:189], 0
	v_mfma_f32_16x16x32_bf16 v[100:103], v[170:173], v[194:197], 0
	v_mfma_f32_16x16x32_bf16 v[96:99], v[178:181], v[194:197], 0
	v_mfma_f32_16x16x32_bf16 v[84:87], v[170:173], v[202:205], 0
	v_mfma_f32_16x16x32_bf16 v[80:83], v[178:181], v[202:205], 0
	v_mfma_f32_16x16x32_bf16 v[68:71], v[170:173], v[214:217], 0
	v_mfma_f32_16x16x32_bf16 v[64:67], v[178:181], v[214:217], 0
	v_mfma_f32_16x16x32_bf16 v[116:119], v[174:177], v[190:193], v[116:119]
	v_mfma_f32_16x16x32_bf16 v[112:115], v[182:185], v[190:193], v[112:115]
	v_mfma_f32_16x16x32_bf16 v[100:103], v[174:177], v[198:201], v[100:103]
	v_mfma_f32_16x16x32_bf16 v[96:99], v[182:185], v[198:201], v[96:99]
	v_mfma_f32_16x16x32_bf16 v[84:87], v[174:177], v[206:209], v[84:87]
	v_mfma_f32_16x16x32_bf16 v[80:83], v[182:185], v[206:209], v[80:83]
	v_mfma_f32_16x16x32_bf16 v[68:71], v[174:177], v[218:221], v[68:71]
	v_mfma_f32_16x16x32_bf16 v[64:67], v[182:185], v[218:221], v[64:67]
	s_setprio 0
	s_barrier
	s_add_i32 s57, s51, s20
	v_lshl_add_u64 v[210:211], s[38:39], 0, v[130:131]
	s_mov_b32 m0, s57
	ds_read_b128 v[186:189], v155 offset:16384
	ds_read_b128 v[190:193], v155 offset:17408
	ds_read_b128 v[194:197], v155 offset:18432
	ds_read_b128 v[198:201], v155 offset:19456
	ds_read_b128 v[202:205], v155 offset:20480
	ds_read_b128 v[206:209], v155 offset:21504
	ds_read_b128 v[214:217], v155 offset:22528
	ds_read_b128 v[218:221], v155 offset:23552
	global_load_lds_dwordx4 v[210:211], off
	s_add_i32 m0, s57, 0x2000
	s_add_u32 s58, s38, 0x40000
	v_lshl_add_u64 v[222:223], s[38:39], 0, v[134:135]
	s_addc_u32 s59, s39, 0
	s_add_i32 s57, s52, s20
	global_load_lds_dwordx4 v[222:223], off
	v_lshl_add_u64 v[224:225], s[58:59], 0, v[130:131]
	s_mov_b32 m0, s57
	v_lshl_add_u64 v[226:227], s[40:41], 0, v[132:133]
	global_load_lds_dwordx4 v[224:225], off
	v_lshl_add_u64 v[224:225], s[58:59], 0, v[134:135]
	s_add_i32 m0, s57, 0x2000
	s_nop 0
	global_load_lds_dwordx4 v[224:225], off
	v_lshl_add_u64 v[224:225], s[40:41], 0, v[128:129]
	s_mov_b32 m0, s44
	s_nop 0
	global_load_lds_dwordx4 v[224:225], off
	s_mov_b32 m0, s45
	s_nop 0
	global_load_lds_dwordx4 v[226:227], off
	s_waitcnt vmcnt(8)
	s_waitcnt lgkmcnt(0)
	s_barrier
; #define PG8_STAGE(bufoff, gbase, voff) do { _Pragma("unroll") for (int _i = 0; _i < 2; ++_i) \
;         __builtin_amdgcn_global_load_lds((const unsigned*)((const char*)(gbase) + (voff)[_i]), (PG8_LAS unsigned*)(lds + (bufoff) + ldsw + _i * 8192), 16, 0, 0); } while (0)
; #define PG8_LDA(dst, b, h) do { _Pragma("unroll") for (int m = 0; m < 4; ++m) _Pragma("unroll") for (int k = 0; k < 2; ++k) dst[m][k] = *(const PG8_LAS bf16x8*)(lds + PG8_SA(b, h) + aoff + m * 2048 + k * 1024); } while (0)
; #define PG8_LDB(dst, b, h) do { _Pragma("unroll") for (int n = 0; n < 2; ++n) _Pragma("unroll") for (int k = 0; k < 2; ++k) dst[n][k] = *(const PG8_LAS bf16x8*)(lds + PG8_SB(b, h) + boff + n * 2048 + k * 1024); } while (0)
; #define PG8_MMA(ai, bj, At, Bt) do { __builtin_amdgcn_s_setprio(1); _Pragma("unroll") for (int m = 0; m < 4; ++m) _Pragma("unroll") for (int n = 0; n < 2; ++n) _Pragma("unroll") for (int k = 0; k < 2; ++k) \
;         acc[ai][bj][m][n] = __builtin_amdgcn_mfma_f32_16x16x32_bf16(Bt[n][k], At[m][k], acc[ai][bj][m][n], 0, 0, 0); __builtin_amdgcn_s_setprio(0); } while (0)
; #define PG8_WAIT_V(n) asm volatile("s_waitcnt vmcnt(" #n ")" ::: "memory")
; #define PG8_WAIT_L(n) asm volatile("s_waitcnt lgkmcnt(" #n ")" ::: "memory")
; #define PG8_BAR __builtin_amdgcn_s_barrier()
; #define PG8_SCHED __builtin_amdgcn_sched_barrier(0)
; template <class Epi, class Sched, bool ALIGN_EPI = false, bool SP2 = false>
; __device__ __forceinline__ void gemm_phase(PG8_LAS unsigned char* lds, const Gemm g, const Sched& S, const Epi& E, const int wv  ) {
;     ...
;             PG8_WAIT_V(8); PG8_WAIT_L(0); PG8_BAR; PG8_MMA(1, 0, At, B0); PG8_MMA(1, 1, At, B1); PG8_BAR; PG8_SCHED;
;             PG8_LDB(B0, 1, 0); PG8_LDB(B1, 1, 1); PG8_SCHED; PG8_LDA(At, 1, 0); PG8_STAGE(PG8_SA(0, 1), a2 + hstep, voffA);
;             PG8_WAIT_V(8); PG8_WAIT_L(0); PG8_BAR; PG8_MMA(0, 0, At, B0); PG8_MMA(0, 1, At, B1); PG8_BAR; PG8_SCHED;
	s_setprio 1
	s_waitcnt lgkmcnt(0)
	v_mfma_f32_16x16x32_bf16 v[60:63], v[144:147], v[186:189], 0
	v_mfma_f32_16x16x32_bf16 v[56:59], v[162:165], v[186:189], 0
	v_mfma_f32_16x16x32_bf16 v[44:47], v[144:147], v[194:197], 0
	v_mfma_f32_16x16x32_bf16 v[40:43], v[162:165], v[194:197], 0
	v_mfma_f32_16x16x32_bf16 v[28:31], v[144:147], v[202:205], 0
	v_mfma_f32_16x16x32_bf16 v[24:27], v[162:165], v[202:205], 0
	v_mfma_f32_16x16x32_bf16 v[12:15], v[144:147], v[214:217], 0
	v_mfma_f32_16x16x32_bf16 v[8:11], v[162:165], v[214:217], 0
	v_mfma_f32_16x16x32_bf16 v[60:63], v[158:161], v[190:193], v[60:63]
	v_mfma_f32_16x16x32_bf16 v[56:59], v[166:169], v[190:193], v[56:59]
	v_mfma_f32_16x16x32_bf16 v[44:47], v[158:161], v[198:201], v[44:47]
	v_mfma_f32_16x16x32_bf16 v[40:43], v[166:169], v[198:201], v[40:43]
	v_mfma_f32_16x16x32_bf16 v[28:31], v[158:161], v[206:209], v[28:31]
	v_mfma_f32_16x16x32_bf16 v[24:27], v[166:169], v[206:209], v[24:27]
	v_mfma_f32_16x16x32_bf16 v[12:15], v[158:161], v[218:221], v[12:15]
	v_mfma_f32_16x16x32_bf16 v[8:11], v[166:169], v[218:221], v[8:11]
	s_setprio 0
	s_setprio 1
	v_mfma_f32_16x16x32_bf16 v[52:55], v[170:173], v[186:189], 0
	v_mfma_f32_16x16x32_bf16 v[48:51], v[178:181], v[186:189], 0
	v_mfma_f32_16x16x32_bf16 v[36:39], v[170:173], v[194:197], 0
	v_mfma_f32_16x16x32_bf16 v[32:35], v[178:181], v[194:197], 0
	v_mfma_f32_16x16x32_bf16 v[20:23], v[170:173], v[202:205], 0
	v_mfma_f32_16x16x32_bf16 v[16:19], v[178:181], v[202:205], 0
	v_mfma_f32_16x16x32_bf16 v[4:7], v[170:173], v[214:217], 0
	v_mfma_f32_16x16x32_bf16 v[0:3], v[178:181], v[214:217], 0
	v_mfma_f32_16x16x32_bf16 v[52:55], v[174:177], v[190:193], v[52:55]
	v_mfma_f32_16x16x32_bf16 v[48:51], v[182:185], v[190:193], v[48:51]
	v_mfma_f32_16x16x32_bf16 v[36:39], v[174:177], v[198:201], v[36:39]
	v_mfma_f32_16x16x32_bf16 v[32:35], v[182:185], v[198:201], v[32:35]
	v_mfma_f32_16x16x32_bf16 v[20:23], v[174:177], v[206:209], v[20:23]
	v_mfma_f32_16x16x32_bf16 v[16:19], v[182:185], v[206:209], v[16:19]
	v_mfma_f32_16x16x32_bf16 v[4:7], v[174:177], v[218:221], v[4:7]
	v_mfma_f32_16x16x32_bf16 v[0:3], v[182:185], v[218:221], v[0:3]
	s_setprio 0
	s_barrier
	s_add_i32 s57, 0, 0x18000
	v_add_u32_e32 v148, s57, v150
	s_add_i32 s58, 0, 0x1c000
	ds_read_b128 v[144:147], v148
	ds_read_b128 v[158:161], v148 offset:1024
	ds_read_b128 v[162:165], v148 offset:2048
	ds_read_b128 v[166:169], v148 offset:3072
	v_add_u32_e32 v148, s58, v150
	ds_read_b128 v[170:173], v148
	ds_read_b128 v[174:177], v148 offset:1024
	ds_read_b128 v[178:181], v148 offset:2048
	ds_read_b128 v[182:185], v148 offset:3072
	s_add_u32 s40, s40, 0x40000
	s_addc_u32 s41, s41, 0
	s_mov_b32 m0, s46
	v_lshl_add_u64 v[228:229], s[40:41], 0, v[128:129]
	ds_read_b128 v[186:189], v155 offset:32768
	ds_read_b128 v[190:193], v155 offset:33792
	ds_read_b128 v[194:197], v155 offset:34816
	ds_read_b128 v[198:201], v155 offset:35840
	ds_read_b128 v[202:205], v155 offset:36864
	ds_read_b128 v[206:209], v155 offset:37888
	ds_read_b128 v[214:217], v155 offset:38912
	ds_read_b128 v[218:221], v155 offset:39936
	global_load_lds_dwordx4 v[228:229], off
	v_lshl_add_u64 v[228:229], s[40:41], 0, v[132:133]
	s_mov_b32 m0, s47
	s_nop 0
	global_load_lds_dwordx4 v[228:229], off
	s_waitcnt vmcnt(8)
	s_waitcnt lgkmcnt(0)
	s_barrier
	s_setprio 1
	s_waitcnt lgkmcnt(0)
	v_mfma_f32_16x16x32_bf16 v[124:127], v[144:147], v[186:189], v[124:127]
	v_mfma_f32_16x16x32_bf16 v[120:123], v[162:165], v[186:189], v[120:123]
	v_mfma_f32_16x16x32_bf16 v[108:111], v[144:147], v[194:197], v[108:111]
	v_mfma_f32_16x16x32_bf16 v[104:107], v[162:165], v[194:197], v[104:107]
	v_mfma_f32_16x16x32_bf16 v[92:95], v[144:147], v[202:205], v[92:95]
	v_mfma_f32_16x16x32_bf16 v[88:91], v[162:165], v[202:205], v[88:91]
	v_mfma_f32_16x16x32_bf16 v[76:79], v[144:147], v[214:217], v[76:79]
	v_mfma_f32_16x16x32_bf16 v[72:75], v[162:165], v[214:217], v[72:75]
	v_mfma_f32_16x16x32_bf16 v[124:127], v[158:161], v[190:193], v[124:127]
	v_mfma_f32_16x16x32_bf16 v[120:123], v[166:169], v[190:193], v[120:123]
	v_mfma_f32_16x16x32_bf16 v[108:111], v[158:161], v[198:201], v[108:111]
	v_mfma_f32_16x16x32_bf16 v[104:107], v[166:169], v[198:201], v[104:107]
	v_mfma_f32_16x16x32_bf16 v[92:95], v[158:161], v[206:209], v[92:95]
	v_mfma_f32_16x16x32_bf16 v[88:91], v[166:169], v[206:209], v[88:91]
	v_mfma_f32_16x16x32_bf16 v[76:79], v[158:161], v[218:221], v[76:79]
	v_mfma_f32_16x16x32_bf16 v[72:75], v[166:169], v[218:221], v[72:75]
	s_setprio 0
	s_setprio 1
	v_mfma_f32_16x16x32_bf16 v[116:119], v[170:173], v[186:189], v[116:119]
	v_mfma_f32_16x16x32_bf16 v[112:115], v[178:181], v[186:189], v[112:115]
	v_mfma_f32_16x16x32_bf16 v[100:103], v[170:173], v[194:197], v[100:103]
	v_mfma_f32_16x16x32_bf16 v[96:99], v[178:181], v[194:197], v[96:99]
	v_mfma_f32_16x16x32_bf16 v[84:87], v[170:173], v[202:205], v[84:87]
	v_mfma_f32_16x16x32_bf16 v[80:83], v[178:181], v[202:205], v[80:83]
	v_mfma_f32_16x16x32_bf16 v[68:71], v[170:173], v[214:217], v[68:71]
	v_mfma_f32_16x16x32_bf16 v[64:67], v[178:181], v[214:217], v[64:67]
	v_mfma_f32_16x16x32_bf16 v[116:119], v[174:177], v[190:193], v[116:119]
	v_mfma_f32_16x16x32_bf16 v[112:115], v[182:185], v[190:193], v[112:115]
	v_mfma_f32_16x16x32_bf16 v[100:103], v[174:177], v[198:201], v[100:103]
	v_mfma_f32_16x16x32_bf16 v[96:99], v[182:185], v[198:201], v[96:99]
	v_mfma_f32_16x16x32_bf16 v[84:87], v[174:177], v[206:209], v[84:87]
	v_mfma_f32_16x16x32_bf16 v[80:83], v[182:185], v[206:209], v[80:83]
	v_mfma_f32_16x16x32_bf16 v[68:71], v[174:177], v[218:221], v[68:71]
	v_mfma_f32_16x16x32_bf16 v[64:67], v[182:185], v[218:221], v[64:67]
	s_setprio 0
	s_barrier
; #define PG8_STAGE(bufoff, gbase, voff) do { _Pragma("unroll") for (int _i = 0; _i < 2; ++_i) \
;         __builtin_amdgcn_global_load_lds((const unsigned*)((const char*)(gbase) + (voff)[_i]), (PG8_LAS unsigned*)(lds + (bufoff) + ldsw + _i * 8192), 16, 0, 0); } while (0)
; #define PG8_LDA(dst, b, h) do { _Pragma("unroll") for (int m = 0; m < 4; ++m) _Pragma("unroll") for (int k = 0; k < 2; ++k) dst[m][k] = *(const PG8_LAS bf16x8*)(lds + PG8_SA(b, h) + aoff + m * 2048 + k * 1024); } while (0)
; #define PG8_MMA(ai, bj, At, Bt) do { __builtin_amdgcn_s_setprio(1); _Pragma("unroll") for (int m = 0; m < 4; ++m) _Pragma("unroll") for (int n = 0; n < 2; ++n) _Pragma("unroll") for (int k = 0; k < 2; ++k) \
;         acc[ai][bj][m][n] = __builtin_amdgcn_mfma_f32_16x16x32_bf16(Bt[n][k], At[m][k], acc[ai][bj][m][n], 0, 0, 0); __builtin_amdgcn_s_setprio(0); } while (0)
; #define PG8_WAIT_V(n) asm volatile("s_waitcnt vmcnt(" #n ")" ::: "memory")
; #define PG8_WAIT_L(n) asm volatile("s_waitcnt lgkmcnt(" #n ")" ::: "memory")
; #define PG8_BAR __builtin_amdgcn_s_barrier()
; #define PG8_SCHED __builtin_amdgcn_sched_barrier(0)
; template <class Epi, class Sched, bool ALIGN_EPI = false, bool SP2 = false>
; __device__ __forceinline__ void gemm_phase(PG8_LAS unsigned char* lds, const Gemm g, const Sched& S, const Epi& E, const int wv  ) {
;     ...
;         for (int t = 0; t < nt; t += 2) {
;     ...
;             PG8_LDA(At, 1, 1); PG8_STAGE(PG8_SB(1, 0), b3, voffB); PG8_STAGE(PG8_SB(1, 1), b3 + hstep, voffB); PG8_STAGE(PG8_SA(1, 0), a3, voffA);
;             PG8_WAIT_V(8); PG8_WAIT_L(0); PG8_BAR; PG8_MMA(1, 0, At, B0); PG8_MMA(1, 1, At, B1); PG8_BAR; PG8_SCHED;
	s_add_i32 s40, s57, s20
	v_lshl_add_u64 v[210:211], v[210:211], 0, s[16:17]
	s_mov_b32 m0, s40
	ds_read_b128 v[186:189], v155 offset:49152
	ds_read_b128 v[190:193], v155 offset:50176
	ds_read_b128 v[194:197], v155 offset:51200
	ds_read_b128 v[198:201], v155 offset:52224
	ds_read_b128 v[202:205], v155 offset:53248
	ds_read_b128 v[206:209], v155 offset:54272
	ds_read_b128 v[214:217], v155 offset:55296
	ds_read_b128 v[218:221], v155 offset:56320
	global_load_lds_dwordx4 v[210:211], off
	s_add_i32 m0, s40, 0x2000
	s_add_u32 s38, s38, 0x40080
	v_lshl_add_u64 v[210:211], v[222:223], 0, s[16:17]
	s_addc_u32 s39, s39, 0
	s_add_i32 s40, s58, s20
	global_load_lds_dwordx4 v[210:211], off
	v_lshl_add_u64 v[210:211], s[38:39], 0, v[130:131]
	s_mov_b32 m0, s40
	s_nop 0
	global_load_lds_dwordx4 v[210:211], off
	v_lshl_add_u64 v[210:211], s[38:39], 0, v[134:135]
	s_add_i32 m0, s40, 0x2000
	s_nop 0
	global_load_lds_dwordx4 v[210:211], off
	v_lshl_add_u64 v[210:211], v[224:225], 0, s[16:17]
	s_mov_b32 m0, s49
	s_nop 0
	global_load_lds_dwordx4 v[210:211], off
	v_lshl_add_u64 v[210:211], v[226:227], 0, s[16:17]
	s_mov_b32 m0, s50
	s_nop 0
	global_load_lds_dwordx4 v[210:211], off
	s_waitcnt vmcnt(8)
	s_waitcnt lgkmcnt(0)
	s_barrier
	s_setprio 1
	s_waitcnt lgkmcnt(0)
	v_mfma_f32_16x16x32_bf16 v[60:63], v[144:147], v[186:189], v[60:63]
	v_mfma_f32_16x16x32_bf16 v[56:59], v[162:165], v[186:189], v[56:59]
	v_mfma_f32_16x16x32_bf16 v[44:47], v[144:147], v[194:197], v[44:47]
	v_mfma_f32_16x16x32_bf16 v[40:43], v[162:165], v[194:197], v[40:43]
	v_mfma_f32_16x16x32_bf16 v[28:31], v[144:147], v[202:205], v[28:31]
	v_mfma_f32_16x16x32_bf16 v[24:27], v[162:165], v[202:205], v[24:27]
	v_mfma_f32_16x16x32_bf16 v[12:15], v[144:147], v[214:217], v[12:15]
	v_mfma_f32_16x16x32_bf16 v[8:11], v[162:165], v[214:217], v[8:11]
	v_mfma_f32_16x16x32_bf16 v[60:63], v[158:161], v[190:193], v[60:63]
	v_mfma_f32_16x16x32_bf16 v[56:59], v[166:169], v[190:193], v[56:59]
	v_mfma_f32_16x16x32_bf16 v[44:47], v[158:161], v[198:201], v[44:47]
	v_mfma_f32_16x16x32_bf16 v[40:43], v[166:169], v[198:201], v[40:43]
	v_mfma_f32_16x16x32_bf16 v[28:31], v[158:161], v[206:209], v[28:31]
	v_mfma_f32_16x16x32_bf16 v[24:27], v[166:169], v[206:209], v[24:27]
	v_mfma_f32_16x16x32_bf16 v[12:15], v[158:161], v[218:221], v[12:15]
	v_mfma_f32_16x16x32_bf16 v[8:11], v[166:169], v[218:221], v[8:11]
	s_setprio 0
	s_setprio 1
	v_mfma_f32_16x16x32_bf16 v[52:55], v[170:173], v[186:189], v[52:55]
	v_mfma_f32_16x16x32_bf16 v[48:51], v[178:181], v[186:189], v[48:51]
	v_mfma_f32_16x16x32_bf16 v[36:39], v[170:173], v[194:197], v[36:39]
	v_mfma_f32_16x16x32_bf16 v[32:35], v[178:181], v[194:197], v[32:35]
	v_mfma_f32_16x16x32_bf16 v[20:23], v[170:173], v[202:205], v[20:23]
	v_mfma_f32_16x16x32_bf16 v[16:19], v[178:181], v[202:205], v[16:19]
	v_mfma_f32_16x16x32_bf16 v[4:7], v[170:173], v[214:217], v[4:7]
	v_mfma_f32_16x16x32_bf16 v[0:3], v[178:181], v[214:217], v[0:3]
	v_mfma_f32_16x16x32_bf16 v[52:55], v[174:177], v[190:193], v[52:55]
	v_mfma_f32_16x16x32_bf16 v[48:51], v[182:185], v[190:193], v[48:51]
	v_mfma_f32_16x16x32_bf16 v[36:39], v[174:177], v[198:201], v[36:39]
	v_mfma_f32_16x16x32_bf16 v[32:35], v[182:185], v[198:201], v[32:35]
	v_mfma_f32_16x16x32_bf16 v[20:23], v[174:177], v[206:209], v[20:23]
	v_mfma_f32_16x16x32_bf16 v[16:19], v[182:185], v[206:209], v[16:19]
	v_mfma_f32_16x16x32_bf16 v[4:7], v[174:177], v[218:221], v[4:7]
	v_mfma_f32_16x16x32_bf16 v[0:3], v[182:185], v[218:221], v[0:3]
	s_setprio 0
	s_barrier
	s_add_i32 s56, s56, 2
	s_add_u32 s0, s0, 0x100
	s_addc_u32 s1, s1, 0
	s_add_u32 s27, s27, 0x100
	s_addc_u32 s29, s29, 0
	s_cmp_gt_u32 s56, 13

; #define PG8_STAGE(bufoff, gbase, voff) do { _Pragma("unroll") for (int _i = 0; _i < 2; ++_i) \
;         __builtin_amdgcn_global_load_lds((const unsigned*)((const char*)(gbase) + (voff)[_i]), (PG8_LAS unsigned*)(lds + (bufoff) + ldsw + _i * 8192), 16, 0, 0); } while (0)
; #define PG8_LDA(dst, b, h) do { _Pragma("unroll") for (int m = 0; m < 4; ++m) _Pragma("unroll") for (int k = 0; k < 2; ++k) dst[m][k] = *(const PG8_LAS bf16x8*)(lds + PG8_SA(b, h) + aoff + m * 2048 + k * 1024); } while (0)
; #define PG8_LDB(dst, b, h) do { _Pragma("unroll") for (int n = 0; n < 2; ++n) _Pragma("unroll") for (int k = 0; k < 2; ++k) dst[n][k] = *(const PG8_LAS bf16x8*)(lds + PG8_SB(b, h) + boff + n * 2048 + k * 1024); } while (0)
; #define PG8_MMA(ai, bj, At, Bt) do { __builtin_amdgcn_s_setprio(1); _Pragma("unroll") for (int m = 0; m < 4; ++m) _Pragma("unroll") for (int n = 0; n < 2; ++n) _Pragma("unroll") for (int k = 0; k < 2; ++k) \
;         acc[ai][bj][m][n] = __builtin_amdgcn_mfma_f32_16x16x32_bf16(Bt[n][k], At[m][k], acc[ai][bj][m][n], 0, 0, 0); __builtin_amdgcn_s_setprio(0); } while (0)
; template <class Epi, class Sched, bool ALIGN_EPI = false, bool SP2 = false>
; __device__ __forceinline__ void gemm_phase(PG8_LAS unsigned char* lds, const Gemm g, const Sched& S, const Epi& E, const int wv  ) {
;     ...
;         const bool has_next = S.next(ui + 1, nxt);
;         const char* nA = has_next ? (const char*)g.A + (size_t)nxt.pm * tstep : cA; const char* nB = has_next ? (const char*)g.Bt + (size_t)nxt.pn * tstep : cB;
;         for (int t = 0; t < nt; t += 2) {
;             const bool last = (t == nt - 2);
;             const char* a1 = cA + (size_t)(t + 1) * kstep;
;             const char* a2 = last ? nA : cA + (size_t)(t + 2) * kstep; const char* b2 = last ? nB : cB + (size_t)(t + 2) * kstep;
;             const char* a3 = a2 + kstep; const char* b3 = b2 + kstep;
;             if (last && has_next) S.a_ready(nxt);
;             if constexpr (SP2) {
;             PG8_LDB(B0, 0, 0); PG8_LDB(B1, 0, 1); PG8_SCHED; PG8_LDA(At, 0, 0); PG8_STAGE(PG8_SA(1, 1), a1 + hstep, voffA);
;             PG8_WAIT_V(8); PG8_WAIT_L(0); PG8_BAR; PG8_MMA(0, 0, At, B0); PG8_MMA(0, 1, At, B1); PG8_BAR; PG8_SCHED;
;             PG8_LDA(At, 0, 1); PG8_STAGE(PG8_SB(0, 0), b2, voffB); PG8_STAGE(PG8_SB(0, 1), b2 + hstep, voffB); PG8_STAGE(PG8_SA(0, 0), a2, voffA);
.LBB0_1455:
	s_ashr_i32 s27, s26, 31
	s_lshl_b64 s[28:29], s[26:27], 21
	s_add_u32 s28, s2, s28
	s_addc_u32 s29, s3, s29
	s_and_b64 s[30:31], s[6:7], exec
	s_cselect_b32 s27, s29, s37
	s_cselect_b32 s35, s28, s36
	s_ashr_i32 s25, s24, 31
	s_lshl_b64 s[30:31], s[24:25], 21
	s_add_u32 s30, s20, s30
	s_addc_u32 s31, s21, s31
	s_and_b64 s[40:41], s[6:7], exec
	s_cselect_b32 s25, s31, s39
	s_cselect_b32 s54, s30, s38
	s_add_u32 s36, s36, 0x100080
	s_addc_u32 s37, s37, 0
	s_add_u32 s55, s38, 0x100
	s_addc_u32 s56, s39, 0
	s_mov_b32 s57, -2
	s_waitcnt lgkmcnt(0)
	ds_read_b128 v[128:131], v191
	ds_read_b128 v[132:135], v191 offset:1024
	ds_read_b128 v[136:139], v191 offset:2048
	ds_read_b128 v[140:143], v191 offset:3072
	ds_read_b128 v[144:147], v192
	ds_read_b128 v[148:151], v192 offset:1024
	ds_read_b128 v[168:171], v192 offset:2048
	ds_read_b128 v[172:175], v192 offset:3072
	s_add_u32 s38, s36, 0xfff00080
	s_addc_u32 s39, s37, -1
	s_cmp_eq_u32 s57, 60
	s_cselect_b32 s41, s27, s39
	s_cselect_b32 s40, s35, s38
	s_cselect_b32 s39, s25, s56
	s_cselect_b32 s38, s54, s55
	v_lshl_add_u64 v[184:185], s[36:37], 0, v[160:161]
	s_add_i32 m0, s42, 0xc000
	ds_read_b128 v[176:179], v193
	ds_read_b128 v[180:183], v193 offset:1024
	ds_read_b128 v[194:197], v193 offset:2048
	ds_read_b128 v[198:201], v193 offset:3072
	ds_read_b128 v[202:205], v193 offset:4096
	ds_read_b128 v[206:209], v193 offset:5120
	ds_read_b128 v[214:217], v193 offset:6144
	ds_read_b128 v[218:221], v193 offset:7168
	global_load_lds_dwordx4 v[184:185], off
	v_lshl_add_u64 v[184:185], s[36:37], 0, v[162:163]
	s_add_i32 m0, s42, 0xe000
	s_nop 0
	global_load_lds_dwordx4 v[184:185], off
	s_waitcnt vmcnt(8)
	s_waitcnt lgkmcnt(0)
	s_barrier
	s_setprio 1
	s_waitcnt lgkmcnt(0)
	v_mfma_f32_16x16x32_bf16 v[124:127], v[128:131], v[176:179], 0
	v_mfma_f32_16x16x32_bf16 v[120:123], v[136:139], v[176:179], 0
	v_mfma_f32_16x16x32_bf16 v[108:111], v[128:131], v[194:197], 0
	v_mfma_f32_16x16x32_bf16 v[104:107], v[136:139], v[194:197], 0
	v_mfma_f32_16x16x32_bf16 v[92:95], v[128:131], v[202:205], 0
	v_mfma_f32_16x16x32_bf16 v[88:91], v[136:139], v[202:205], 0
	v_mfma_f32_16x16x32_bf16 v[76:79], v[128:131], v[214:217], 0
	v_mfma_f32_16x16x32_bf16 v[72:75], v[136:139], v[214:217], 0
	v_mfma_f32_16x16x32_bf16 v[124:127], v[132:135], v[180:183], v[124:127]
	v_mfma_f32_16x16x32_bf16 v[120:123], v[140:143], v[180:183], v[120:123]
	v_mfma_f32_16x16x32_bf16 v[108:111], v[132:135], v[198:201], v[108:111]
	v_mfma_f32_16x16x32_bf16 v[104:107], v[140:143], v[198:201], v[104:107]
	v_mfma_f32_16x16x32_bf16 v[92:95], v[132:135], v[206:209], v[92:95]
	v_mfma_f32_16x16x32_bf16 v[88:91], v[140:143], v[206:209], v[88:91]
	v_mfma_f32_16x16x32_bf16 v[76:79], v[132:135], v[218:221], v[76:79]
	v_mfma_f32_16x16x32_bf16 v[72:75], v[140:143], v[218:221], v[72:75]
	s_setprio 0
	s_setprio 1
	v_mfma_f32_16x16x32_bf16 v[116:119], v[144:147], v[176:179], 0
	v_mfma_f32_16x16x32_bf16 v[112:115], v[168:171], v[176:179], 0
	v_mfma_f32_16x16x32_bf16 v[100:103], v[144:147], v[194:197], 0
	v_mfma_f32_16x16x32_bf16 v[96:99], v[168:171], v[194:197], 0
	v_mfma_f32_16x16x32_bf16 v[84:87], v[144:147], v[202:205], 0
	v_mfma_f32_16x16x32_bf16 v[80:83], v[168:171], v[202:205], 0
	v_mfma_f32_16x16x32_bf16 v[68:71], v[144:147], v[214:217], 0
	v_mfma_f32_16x16x32_bf16 v[64:67], v[168:171], v[214:217], 0
	v_mfma_f32_16x16x32_bf16 v[116:119], v[148:151], v[180:183], v[116:119]
	v_mfma_f32_16x16x32_bf16 v[112:115], v[172:175], v[180:183], v[112:115]
	v_mfma_f32_16x16x32_bf16 v[100:103], v[148:151], v[198:201], v[100:103]
	v_mfma_f32_16x16x32_bf16 v[96:99], v[172:175], v[198:201], v[96:99]
	v_mfma_f32_16x16x32_bf16 v[84:87], v[148:151], v[206:209], v[84:87]
	v_mfma_f32_16x16x32_bf16 v[80:83], v[172:175], v[206:209], v[80:83]
	v_mfma_f32_16x16x32_bf16 v[68:71], v[148:151], v[218:221], v[68:71]
	v_mfma_f32_16x16x32_bf16 v[64:67], v[172:175], v[218:221], v[64:67]
	s_setprio 0
	s_barrier
	s_add_i32 s58, s51, s33
	v_lshl_add_u64 v[184:185], s[38:39], 0, v[154:155]
	s_mov_b32 m0, s58
	ds_read_b128 v[176:179], v193 offset:16384
	ds_read_b128 v[180:183], v193 offset:17408
	ds_read_b128 v[194:197], v193 offset:18432
	ds_read_b128 v[198:201], v193 offset:19456
	ds_read_b128 v[202:205], v193 offset:20480
	ds_read_b128 v[206:209], v193 offset:21504
	ds_read_b128 v[214:217], v193 offset:22528
	ds_read_b128 v[218:221], v193 offset:23552
	global_load_lds_dwordx4 v[184:185], off
	s_add_i32 m0, s58, 0x2000
	s_add_u32 s58, s38, 0x100000
	v_lshl_add_u64 v[210:211], s[38:39], 0, v[158:159]
	s_addc_u32 s59, s39, 0
	s_add_i32 s60, s52, s33
	global_load_lds_dwordx4 v[210:211], off
	v_lshl_add_u64 v[222:223], s[58:59], 0, v[154:155]
	s_mov_b32 m0, s60
	v_lshl_add_u64 v[224:225], s[40:41], 0, v[156:157]
	global_load_lds_dwordx4 v[222:223], off
	v_lshl_add_u64 v[222:223], s[58:59], 0, v[158:159]
	s_add_i32 m0, s60, 0x2000
	s_nop 0
	global_load_lds_dwordx4 v[222:223], off
	v_lshl_add_u64 v[222:223], s[40:41], 0, v[152:153]
	s_mov_b32 m0, s42
	s_nop 0
	global_load_lds_dwordx4 v[222:223], off
	s_mov_b32 m0, s43
	s_nop 0
	global_load_lds_dwordx4 v[224:225], off
	s_waitcnt vmcnt(8)
	s_waitcnt lgkmcnt(0)
	s_barrier
; #define PG8_STAGE(bufoff, gbase, voff) do { _Pragma("unroll") for (int _i = 0; _i < 2; ++_i) \
;         __builtin_amdgcn_global_load_lds((const unsigned*)((const char*)(gbase) + (voff)[_i]), (PG8_LAS unsigned*)(lds + (bufoff) + ldsw + _i * 8192), 16, 0, 0); } while (0)
; #define PG8_LDA(dst, b, h) do { _Pragma("unroll") for (int m = 0; m < 4; ++m) _Pragma("unroll") for (int k = 0; k < 2; ++k) dst[m][k] = *(const PG8_LAS bf16x8*)(lds + PG8_SA(b, h) + aoff + m * 2048 + k * 1024); } while (0)
; #define PG8_LDB(dst, b, h) do { _Pragma("unroll") for (int n = 0; n < 2; ++n) _Pragma("unroll") for (int k = 0; k < 2; ++k) dst[n][k] = *(const PG8_LAS bf16x8*)(lds + PG8_SB(b, h) + boff + n * 2048 + k * 1024); } while (0)
; #define PG8_MMA(ai, bj, At, Bt) do { __builtin_amdgcn_s_setprio(1); _Pragma("unroll") for (int m = 0; m < 4; ++m) _Pragma("unroll") for (int n = 0; n < 2; ++n) _Pragma("unroll") for (int k = 0; k < 2; ++k) \
;         acc[ai][bj][m][n] = __builtin_amdgcn_mfma_f32_16x16x32_bf16(Bt[n][k], At[m][k], acc[ai][bj][m][n], 0, 0, 0); __builtin_amdgcn_s_setprio(0); } while (0)
; #define PG8_WAIT_V(n) asm volatile("s_waitcnt vmcnt(" #n ")" ::: "memory")
; #define PG8_WAIT_L(n) asm volatile("s_waitcnt lgkmcnt(" #n ")" ::: "memory")
; #define PG8_BAR __builtin_amdgcn_s_barrier()
; #define PG8_SCHED __builtin_amdgcn_sched_barrier(0)
; template <class Epi, class Sched, bool ALIGN_EPI = false, bool SP2 = false>
; __device__ __forceinline__ void gemm_phase(PG8_LAS unsigned char* lds, const Gemm g, const Sched& S, const Epi& E, const int wv  ) {
;     ...
;             PG8_WAIT_V(8); PG8_WAIT_L(0); PG8_BAR; PG8_MMA(1, 0, At, B0); PG8_MMA(1, 1, At, B1); PG8_BAR; PG8_SCHED;
;             PG8_LDB(B0, 1, 0); PG8_LDB(B1, 1, 1); PG8_SCHED; PG8_LDA(At, 1, 0); PG8_STAGE(PG8_SA(0, 1), a2 + hstep, voffA);
;             PG8_WAIT_V(8); PG8_WAIT_L(0); PG8_BAR; PG8_MMA(0, 0, At, B0); PG8_MMA(0, 1, At, B1); PG8_BAR; PG8_SCHED;
	s_setprio 1
	s_waitcnt lgkmcnt(0)
	v_mfma_f32_16x16x32_bf16 v[60:63], v[128:131], v[176:179], 0
	v_mfma_f32_16x16x32_bf16 v[56:59], v[136:139], v[176:179], 0
	v_mfma_f32_16x16x32_bf16 v[44:47], v[128:131], v[194:197], 0
	v_mfma_f32_16x16x32_bf16 v[40:43], v[136:139], v[194:197], 0
	v_mfma_f32_16x16x32_bf16 v[28:31], v[128:131], v[202:205], 0
	v_mfma_f32_16x16x32_bf16 v[24:27], v[136:139], v[202:205], 0
	v_mfma_f32_16x16x32_bf16 v[12:15], v[128:131], v[214:217], 0
	v_mfma_f32_16x16x32_bf16 v[8:11], v[136:139], v[214:217], 0
	v_mfma_f32_16x16x32_bf16 v[60:63], v[132:135], v[180:183], v[60:63]
	v_mfma_f32_16x16x32_bf16 v[56:59], v[140:143], v[180:183], v[56:59]
	v_mfma_f32_16x16x32_bf16 v[44:47], v[132:135], v[198:201], v[44:47]
	v_mfma_f32_16x16x32_bf16 v[40:43], v[140:143], v[198:201], v[40:43]
	v_mfma_f32_16x16x32_bf16 v[28:31], v[132:135], v[206:209], v[28:31]
	v_mfma_f32_16x16x32_bf16 v[24:27], v[140:143], v[206:209], v[24:27]
	v_mfma_f32_16x16x32_bf16 v[12:15], v[132:135], v[218:221], v[12:15]
	v_mfma_f32_16x16x32_bf16 v[8:11], v[140:143], v[218:221], v[8:11]
	s_setprio 0
	s_setprio 1
	v_mfma_f32_16x16x32_bf16 v[52:55], v[144:147], v[176:179], 0
	v_mfma_f32_16x16x32_bf16 v[48:51], v[168:171], v[176:179], 0
	v_mfma_f32_16x16x32_bf16 v[36:39], v[144:147], v[194:197], 0
	v_mfma_f32_16x16x32_bf16 v[32:35], v[168:171], v[194:197], 0
	v_mfma_f32_16x16x32_bf16 v[20:23], v[144:147], v[202:205], 0
	v_mfma_f32_16x16x32_bf16 v[16:19], v[168:171], v[202:205], 0
	v_mfma_f32_16x16x32_bf16 v[4:7], v[144:147], v[214:217], 0
	v_mfma_f32_16x16x32_bf16 v[0:3], v[168:171], v[214:217], 0
	v_mfma_f32_16x16x32_bf16 v[52:55], v[148:151], v[180:183], v[52:55]
	v_mfma_f32_16x16x32_bf16 v[48:51], v[172:175], v[180:183], v[48:51]
	v_mfma_f32_16x16x32_bf16 v[36:39], v[148:151], v[198:201], v[36:39]
	v_mfma_f32_16x16x32_bf16 v[32:35], v[172:175], v[198:201], v[32:35]
	v_mfma_f32_16x16x32_bf16 v[20:23], v[148:151], v[206:209], v[20:23]
	v_mfma_f32_16x16x32_bf16 v[16:19], v[172:175], v[206:209], v[16:19]
	v_mfma_f32_16x16x32_bf16 v[4:7], v[148:151], v[218:221], v[4:7]
	v_mfma_f32_16x16x32_bf16 v[0:3], v[172:175], v[218:221], v[0:3]
	s_setprio 0
	s_barrier
	s_add_i32 s58, 0, 0x18000
	s_add_i32 s59, 0, 0x1c000
	v_add_u32_e32 v140, s58, v189
	v_add_u32_e32 v172, s59, v189
	ds_read_b128 v[128:131], v140
	ds_read_b128 v[132:135], v140 offset:1024
	ds_read_b128 v[136:139], v140 offset:2048
	ds_read_b128 v[140:143], v140 offset:3072
	ds_read_b128 v[144:147], v172
	ds_read_b128 v[148:151], v172 offset:1024
	ds_read_b128 v[168:171], v172 offset:2048
	ds_read_b128 v[172:175], v172 offset:3072
	s_add_u32 s40, s40, 0x100000
	s_addc_u32 s41, s41, 0
	s_mov_b32 m0, s44
	v_lshl_add_u64 v[226:227], s[40:41], 0, v[152:153]
	ds_read_b128 v[176:179], v193 offset:32768
	ds_read_b128 v[180:183], v193 offset:33792
	ds_read_b128 v[194:197], v193 offset:34816
	ds_read_b128 v[198:201], v193 offset:35840
	ds_read_b128 v[202:205], v193 offset:36864
	ds_read_b128 v[206:209], v193 offset:37888
	ds_read_b128 v[214:217], v193 offset:38912
	ds_read_b128 v[218:221], v193 offset:39936
	global_load_lds_dwordx4 v[226:227], off
	v_lshl_add_u64 v[226:227], s[40:41], 0, v[156:157]
	s_mov_b32 m0, s45
	s_nop 0
	global_load_lds_dwordx4 v[226:227], off
	s_waitcnt vmcnt(8)
	s_waitcnt lgkmcnt(0)
	s_barrier
	s_setprio 1
	s_waitcnt lgkmcnt(0)
	v_mfma_f32_16x16x32_bf16 v[124:127], v[128:131], v[176:179], v[124:127]
	v_mfma_f32_16x16x32_bf16 v[120:123], v[136:139], v[176:179], v[120:123]
	v_mfma_f32_16x16x32_bf16 v[108:111], v[128:131], v[194:197], v[108:111]
	v_mfma_f32_16x16x32_bf16 v[104:107], v[136:139], v[194:197], v[104:107]
	v_mfma_f32_16x16x32_bf16 v[92:95], v[128:131], v[202:205], v[92:95]
	v_mfma_f32_16x16x32_bf16 v[88:91], v[136:139], v[202:205], v[88:91]
	v_mfma_f32_16x16x32_bf16 v[76:79], v[128:131], v[214:217], v[76:79]
	v_mfma_f32_16x16x32_bf16 v[72:75], v[136:139], v[214:217], v[72:75]
	v_mfma_f32_16x16x32_bf16 v[124:127], v[132:135], v[180:183], v[124:127]
	v_mfma_f32_16x16x32_bf16 v[120:123], v[140:143], v[180:183], v[120:123]
	v_mfma_f32_16x16x32_bf16 v[108:111], v[132:135], v[198:201], v[108:111]
	v_mfma_f32_16x16x32_bf16 v[104:107], v[140:143], v[198:201], v[104:107]
	v_mfma_f32_16x16x32_bf16 v[92:95], v[132:135], v[206:209], v[92:95]
	v_mfma_f32_16x16x32_bf16 v[88:91], v[140:143], v[206:209], v[88:91]
	v_mfma_f32_16x16x32_bf16 v[76:79], v[132:135], v[218:221], v[76:79]
	v_mfma_f32_16x16x32_bf16 v[72:75], v[140:143], v[218:221], v[72:75]
	s_setprio 0
	s_setprio 1
	v_mfma_f32_16x16x32_bf16 v[116:119], v[144:147], v[176:179], v[116:119]
	v_mfma_f32_16x16x32_bf16 v[112:115], v[168:171], v[176:179], v[112:115]
	v_mfma_f32_16x16x32_bf16 v[100:103], v[144:147], v[194:197], v[100:103]
	v_mfma_f32_16x16x32_bf16 v[96:99], v[168:171], v[194:197], v[96:99]
	v_mfma_f32_16x16x32_bf16 v[84:87], v[144:147], v[202:205], v[84:87]
	v_mfma_f32_16x16x32_bf16 v[80:83], v[168:171], v[202:205], v[80:83]
	v_mfma_f32_16x16x32_bf16 v[68:71], v[144:147], v[214:217], v[68:71]
	v_mfma_f32_16x16x32_bf16 v[64:67], v[168:171], v[214:217], v[64:67]
	v_mfma_f32_16x16x32_bf16 v[116:119], v[148:151], v[180:183], v[116:119]
	v_mfma_f32_16x16x32_bf16 v[112:115], v[172:175], v[180:183], v[112:115]
	v_mfma_f32_16x16x32_bf16 v[100:103], v[148:151], v[198:201], v[100:103]
	v_mfma_f32_16x16x32_bf16 v[96:99], v[172:175], v[198:201], v[96:99]
	v_mfma_f32_16x16x32_bf16 v[84:87], v[148:151], v[206:209], v[84:87]
	v_mfma_f32_16x16x32_bf16 v[80:83], v[172:175], v[206:209], v[80:83]
	v_mfma_f32_16x16x32_bf16 v[68:71], v[148:151], v[218:221], v[68:71]
	v_mfma_f32_16x16x32_bf16 v[64:67], v[172:175], v[218:221], v[64:67]
	s_setprio 0
	s_barrier
; #define PG8_STAGE(bufoff, gbase, voff) do { _Pragma("unroll") for (int _i = 0; _i < 2; ++_i) \
;         __builtin_amdgcn_global_load_lds((const unsigned*)((const char*)(gbase) + (voff)[_i]), (PG8_LAS unsigned*)(lds + (bufoff) + ldsw + _i * 8192), 16, 0, 0); } while (0)
; #define PG8_LDA(dst, b, h) do { _Pragma("unroll") for (int m = 0; m < 4; ++m) _Pragma("unroll") for (int k = 0; k < 2; ++k) dst[m][k] = *(const PG8_LAS bf16x8*)(lds + PG8_SA(b, h) + aoff + m * 2048 + k * 1024); } while (0)
; #define PG8_MMA(ai, bj, At, Bt) do { __builtin_amdgcn_s_setprio(1); _Pragma("unroll") for (int m = 0; m < 4; ++m) _Pragma("unroll") for (int n = 0; n < 2; ++n) _Pragma("unroll") for (int k = 0; k < 2; ++k) \
;         acc[ai][bj][m][n] = __builtin_amdgcn_mfma_f32_16x16x32_bf16(Bt[n][k], At[m][k], acc[ai][bj][m][n], 0, 0, 0); __builtin_amdgcn_s_setprio(0); } while (0)
; #define PG8_WAIT_V(n) asm volatile("s_waitcnt vmcnt(" #n ")" ::: "memory")
; #define PG8_WAIT_L(n) asm volatile("s_waitcnt lgkmcnt(" #n ")" ::: "memory")
; #define PG8_BAR __builtin_amdgcn_s_barrier()
; #define PG8_SCHED __builtin_amdgcn_sched_barrier(0)
; template <class Epi, class Sched, bool ALIGN_EPI = false, bool SP2 = false>
; __device__ __forceinline__ void gemm_phase(PG8_LAS unsigned char* lds, const Gemm g, const Sched& S, const Epi& E, const int wv  ) {
;     ...
;         for (int t = 0; t < nt; t += 2) {
;     ...
;             PG8_LDA(At, 1, 1); PG8_STAGE(PG8_SB(1, 0), b3, voffB); PG8_STAGE(PG8_SB(1, 1), b3 + hstep, voffB); PG8_STAGE(PG8_SA(1, 0), a3, voffA);
;             PG8_WAIT_V(8); PG8_WAIT_L(0); PG8_BAR; PG8_MMA(1, 0, At, B0); PG8_MMA(1, 1, At, B1); PG8_BAR; PG8_SCHED;
	s_add_i32 s40, s58, s33
	v_lshl_add_u64 v[184:185], v[184:185], 0, s[18:19]
	s_mov_b32 m0, s40
	ds_read_b128 v[176:179], v193 offset:49152
	ds_read_b128 v[180:183], v193 offset:50176
	ds_read_b128 v[194:197], v193 offset:51200
	ds_read_b128 v[198:201], v193 offset:52224
	ds_read_b128 v[202:205], v193 offset:53248
	ds_read_b128 v[206:209], v193 offset:54272
	ds_read_b128 v[214:217], v193 offset:55296
	ds_read_b128 v[218:221], v193 offset:56320
	global_load_lds_dwordx4 v[184:185], off
	s_add_i32 m0, s40, 0x2000
	s_add_u32 s38, s38, 0x100080
	v_lshl_add_u64 v[184:185], v[210:211], 0, s[18:19]
	s_addc_u32 s39, s39, 0
	s_add_i32 s40, s59, s33
	global_load_lds_dwordx4 v[184:185], off
	v_lshl_add_u64 v[184:185], s[38:39], 0, v[154:155]
	s_mov_b32 m0, s40
	s_nop 0
	global_load_lds_dwordx4 v[184:185], off
	v_lshl_add_u64 v[184:185], s[38:39], 0, v[158:159]
	s_add_i32 m0, s40, 0x2000
	s_nop 0
	global_load_lds_dwordx4 v[184:185], off
	v_lshl_add_u64 v[184:185], v[222:223], 0, s[18:19]
	s_mov_b32 m0, s49
	s_nop 0
	global_load_lds_dwordx4 v[184:185], off
	v_lshl_add_u64 v[184:185], v[224:225], 0, s[18:19]
	s_mov_b32 m0, s50
	s_nop 0
	global_load_lds_dwordx4 v[184:185], off
	s_waitcnt vmcnt(8)
	s_waitcnt lgkmcnt(0)
	s_barrier
	s_setprio 1
	s_waitcnt lgkmcnt(0)
	v_mfma_f32_16x16x32_bf16 v[60:63], v[128:131], v[176:179], v[60:63]
	v_mfma_f32_16x16x32_bf16 v[56:59], v[136:139], v[176:179], v[56:59]
	v_mfma_f32_16x16x32_bf16 v[44:47], v[128:131], v[194:197], v[44:47]
	v_mfma_f32_16x16x32_bf16 v[40:43], v[136:139], v[194:197], v[40:43]
	v_mfma_f32_16x16x32_bf16 v[28:31], v[128:131], v[202:205], v[28:31]
	v_mfma_f32_16x16x32_bf16 v[24:27], v[136:139], v[202:205], v[24:27]
	v_mfma_f32_16x16x32_bf16 v[12:15], v[128:131], v[214:217], v[12:15]
	v_mfma_f32_16x16x32_bf16 v[8:11], v[136:139], v[214:217], v[8:11]
	v_mfma_f32_16x16x32_bf16 v[60:63], v[132:135], v[180:183], v[60:63]
	v_mfma_f32_16x16x32_bf16 v[56:59], v[140:143], v[180:183], v[56:59]
	v_mfma_f32_16x16x32_bf16 v[44:47], v[132:135], v[198:201], v[44:47]
	v_mfma_f32_16x16x32_bf16 v[40:43], v[140:143], v[198:201], v[40:43]
	v_mfma_f32_16x16x32_bf16 v[28:31], v[132:135], v[206:209], v[28:31]
	v_mfma_f32_16x16x32_bf16 v[24:27], v[140:143], v[206:209], v[24:27]
	v_mfma_f32_16x16x32_bf16 v[12:15], v[132:135], v[218:221], v[12:15]
	v_mfma_f32_16x16x32_bf16 v[8:11], v[140:143], v[218:221], v[8:11]
	s_setprio 0
	s_setprio 1
	v_mfma_f32_16x16x32_bf16 v[52:55], v[144:147], v[176:179], v[52:55]
	v_mfma_f32_16x16x32_bf16 v[48:51], v[168:171], v[176:179], v[48:51]
	v_mfma_f32_16x16x32_bf16 v[36:39], v[144:147], v[194:197], v[36:39]
	v_mfma_f32_16x16x32_bf16 v[32:35], v[168:171], v[194:197], v[32:35]
	v_mfma_f32_16x16x32_bf16 v[20:23], v[144:147], v[202:205], v[20:23]
	v_mfma_f32_16x16x32_bf16 v[16:19], v[168:171], v[202:205], v[16:19]
	v_mfma_f32_16x16x32_bf16 v[4:7], v[144:147], v[214:217], v[4:7]
	v_mfma_f32_16x16x32_bf16 v[0:3], v[168:171], v[214:217], v[0:3]
	v_mfma_f32_16x16x32_bf16 v[52:55], v[148:151], v[180:183], v[52:55]
	v_mfma_f32_16x16x32_bf16 v[48:51], v[172:175], v[180:183], v[48:51]
	v_mfma_f32_16x16x32_bf16 v[36:39], v[148:151], v[198:201], v[36:39]
	v_mfma_f32_16x16x32_bf16 v[32:35], v[172:175], v[198:201], v[32:35]
	v_mfma_f32_16x16x32_bf16 v[20:23], v[148:151], v[206:209], v[20:23]
	v_mfma_f32_16x16x32_bf16 v[16:19], v[172:175], v[206:209], v[16:19]
	v_mfma_f32_16x16x32_bf16 v[4:7], v[148:151], v[218:221], v[4:7]
	v_mfma_f32_16x16x32_bf16 v[0:3], v[172:175], v[218:221], v[0:3]
	s_setprio 0
	s_barrier
	s_add_i32 s57, s57, 2
	s_add_u32 s36, s36, 0x100
	s_addc_u32 s37, s37, 0
	s_add_u32 s55, s55, 0x100
	s_addc_u32 s56, s56, 0
	s_cmp_gt_u32 s57, 61
